# GEMM loops: 8 of 16 LDS-DMA per iteration converted to SGPR-base form (no VALU address add), plus scan deferral and early-barrier GEMM
# speedup vs baseline: 1.0026x; 1.0026x over previous
; #define PG8_STAGE(bufoff, gbase, voff) do { _Pragma("unroll") for (int _i = 0; _i < 2; ++_i) \
;     __builtin_amdgcn_global_load_lds((const unsigned*)((const char*)(gbase) + (voff)[_i]), (LAS unsigned*)(lds + (bufoff) + ldsw + _i * 8192), 16, 0, 0); } while (0)
; #define PG8_LDA(dst, b, h) do { _Pragma("unroll") for (int m = 0; m < 4; ++m) _Pragma("unroll") for (int k = 0; k < 2; ++k) dst[m][k] = *(const LAS bf16x8*)(lds + PG8_SA(b, h) + aoff + m * 2048 + k * 1024); } while (0)
; #define PG8_LDB(dst, b, h) do { _Pragma("unroll") for (int n = 0; n < 2; ++n) _Pragma("unroll") for (int k = 0; k < 2; ++k) dst[n][k] = *(const LAS bf16x8*)(lds + PG8_SB(b, h) + boff + n * 2048 + k * 1024); } while (0)
; #define PG8_MMA(ai, bj, At, Bt) do { __builtin_amdgcn_s_setprio(1); _Pragma("unroll") for (int m = 0; m < 4; ++m) _Pragma("unroll") for (int n = 0; n < 2; ++n) _Pragma("unroll") for (int k = 0; k < 2; ++k) \
;     acc[ai][bj][m][n] = __builtin_amdgcn_mfma_f32_16x16x32_bf16(Bt[n][k], At[m][k], acc[ai][bj][m][n], 0, 0, 0); __builtin_amdgcn_s_setprio(0); } while (0)
; #define PG8_WAIT_V(n) asm volatile("s_waitcnt vmcnt(" #n ")" ::: "memory")
; #define PG8_BAR __builtin_amdgcn_s_barrier()
; template <class Epi>
; DI void gemm_phase(LAS unsigned char* lds, const Gemm g, const Epi& E) {
;     ...
;     for (int t = 0; t < nt; t += 2) {
;       const bool last = (t == nt - 2);
;       const char* a1 = cA + (size_t)(t + 1) * kstep;
;       const char* a2 = last ? nA : cA + (size_t)(t + 2) * kstep; const char* b2 = last ? nB : cB + (size_t)(t + 2) * kstep;
;       const char* a3 = a2 + kstep; const char* b3 = b2 + kstep;
;       PG8_LDB(B0, 0, 0); PG8_SCHED; PG8_LDA(At, 0, 0); PG8_STAGE(PG8_SA(1, 1), a1 + hstepA, voffA);
;       PG8_WAIT_L(8); PG8_BAR; PG8_WAIT_L(0); PG8_MMA(0, 0, At, B0); PG8_BAR; PG8_SCHED;
;       PG8_LDB(B1, 0, 1); PG8_STAGE(PG8_SB(0, 0), b2, voffB);
;       PG8_BAR; PG8_WAIT_L(0); PG8_MMA(0, 1, At, B1); PG8_BAR;
;       PG8_LDA(At, 0, 1); PG8_STAGE(PG8_SA(0, 0), a2, voffA);
;       PG8_BAR; PG8_WAIT_L(0); PG8_MMA(1, 0, At, B0); PG8_BAR; PG8_SCHED;
;       PG8_STAGE(PG8_SB(0, 1), b2 + hstepB, voffB);
;       PG8_WAIT_V(6); PG8_BAR; PG8_MMA(1, 1, At, B1); PG8_BAR;
;       PG8_LDB(B0, 1, 0); PG8_SCHED; PG8_LDA(At, 1, 0); PG8_STAGE(PG8_SA(0, 1), a2 + hstepA, voffA);
;       PG8_WAIT_L(8); PG8_BAR; PG8_WAIT_L(0); PG8_MMA(0, 0, At, B0); PG8_BAR; PG8_SCHED;
.LBB0_190:
	s_add_u32 s36, s30, 0xfff80080
	s_addc_u32 s37, s31, -1
	s_add_i32 s60, 0, 0x10000
	s_cmp_eq_u32 s59, 28
	s_cselect_b32 s41, s13, s37
	s_cselect_b32 s40, s55, s36
	s_cselect_b32 s37, s3, s58
	s_cselect_b32 s36, s56, s57
	s_add_i32 m0, s27, 0xc000
	ds_read_b128 v[180:183], v145
	ds_read_b128 v[184:187], v145 offset:1024
	ds_read_b128 v[188:191], v145 offset:2048
	ds_read_b128 v[192:195], v145 offset:3072
	ds_read_b128 v[196:199], v145 offset:4096
	ds_read_b128 v[200:203], v145 offset:5120
	ds_read_b128 v[208:211], v145 offset:6144
	ds_read_b128 v[212:215], v145 offset:7168
	global_load_lds_dwordx4 v138, s[30:31]
	s_add_i32 m0, s27, 0xe000
	s_nop 0
	global_load_lds_dwordx4 v140, s[30:31]
	s_waitcnt lgkmcnt(8)
	s_barrier
	s_waitcnt lgkmcnt(0)
	s_setprio 1
	s_waitcnt lgkmcnt(0)
	v_mfma_f32_16x16x32_bf16 v[128:131], v[146:149], v[180:183], v[128:131]
	v_mfma_f32_16x16x32_bf16 v[120:123], v[154:157], v[180:183], v[120:123]
	v_mfma_f32_16x16x32_bf16 v[112:115], v[146:149], v[188:191], v[112:115]
	v_mfma_f32_16x16x32_bf16 v[104:107], v[154:157], v[188:191], v[104:107]
	v_mfma_f32_16x16x32_bf16 v[96:99], v[146:149], v[196:199], v[96:99]
	v_mfma_f32_16x16x32_bf16 v[88:91], v[154:157], v[196:199], v[88:91]
	v_mfma_f32_16x16x32_bf16 v[80:83], v[146:149], v[208:211], v[80:83]
	v_mfma_f32_16x16x32_bf16 v[72:75], v[154:157], v[208:211], v[72:75]
	v_mfma_f32_16x16x32_bf16 v[128:131], v[150:153], v[184:187], v[128:131]
	v_mfma_f32_16x16x32_bf16 v[120:123], v[158:161], v[184:187], v[120:123]
	v_mfma_f32_16x16x32_bf16 v[112:115], v[150:153], v[192:195], v[112:115]
	v_mfma_f32_16x16x32_bf16 v[104:107], v[158:161], v[192:195], v[104:107]
	v_mfma_f32_16x16x32_bf16 v[96:99], v[150:153], v[200:203], v[96:99]
	v_mfma_f32_16x16x32_bf16 v[88:91], v[158:161], v[200:203], v[88:91]
	s_setprio 2
	s_barrier
	v_mfma_f32_16x16x32_bf16 v[80:83], v[150:153], v[212:215], v[80:83]
	v_mfma_f32_16x16x32_bf16 v[72:75], v[158:161], v[212:215], v[72:75]
	s_setprio 0
	s_add_i32 s62, 0, 0x14000
	s_add_i32 s60, s60, s47
	ds_read_b128 v[216:219], v248 offset:16384
	ds_read_b128 v[220:223], v248 offset:17408
	ds_read_b128 v[224:227], v248 offset:18432
	ds_read_b128 v[228:231], v248 offset:19456
	v_lshl_add_u64 v[162:163], s[36:37], 0, v[2:3]
	s_mov_b32 m0, s60
	v_lshl_add_u64 v[232:233], s[36:37], 0, v[132:133]
	global_load_lds_dwordx4 v[162:163], off
	s_add_i32 m0, s60, 0x2000
	s_nop 0
	global_load_lds_dwordx4 v[232:233], off
	s_barrier
	s_waitcnt lgkmcnt(0)
	s_setprio 1
	s_waitcnt lgkmcnt(0)
	v_mfma_f32_16x16x32_bf16 v[124:127], v[216:219], v[180:183], v[124:127]
	v_mfma_f32_16x16x32_bf16 v[116:119], v[224:227], v[180:183], v[116:119]
	v_mfma_f32_16x16x32_bf16 v[108:111], v[216:219], v[188:191], v[108:111]
	v_mfma_f32_16x16x32_bf16 v[100:103], v[224:227], v[188:191], v[100:103]
	v_mfma_f32_16x16x32_bf16 v[92:95], v[216:219], v[196:199], v[92:95]
	v_mfma_f32_16x16x32_bf16 v[84:87], v[224:227], v[196:199], v[84:87]
	v_mfma_f32_16x16x32_bf16 v[76:79], v[216:219], v[208:211], v[76:79]
	v_mfma_f32_16x16x32_bf16 v[68:71], v[224:227], v[208:211], v[68:71]
	v_mfma_f32_16x16x32_bf16 v[124:127], v[220:223], v[184:187], v[124:127]
	v_mfma_f32_16x16x32_bf16 v[116:119], v[228:231], v[184:187], v[116:119]
	v_mfma_f32_16x16x32_bf16 v[108:111], v[220:223], v[192:195], v[108:111]
	v_mfma_f32_16x16x32_bf16 v[100:103], v[228:231], v[192:195], v[100:103]
	v_mfma_f32_16x16x32_bf16 v[92:95], v[220:223], v[200:203], v[92:95]
	v_mfma_f32_16x16x32_bf16 v[84:87], v[228:231], v[200:203], v[84:87]
	s_setprio 2
	s_barrier
	v_mfma_f32_16x16x32_bf16 v[76:79], v[220:223], v[212:215], v[76:79]
	v_mfma_f32_16x16x32_bf16 v[68:71], v[228:231], v[212:215], v[68:71]
	s_setprio 0
	s_mov_b32 m0, s27
	v_lshl_add_u64 v[234:235], s[40:41], 0, v[136:137]
	ds_read_b128 v[180:183], v145 offset:16384
	ds_read_b128 v[184:187], v145 offset:17408
	ds_read_b128 v[188:191], v145 offset:18432
	ds_read_b128 v[192:195], v145 offset:19456
	ds_read_b128 v[196:199], v145 offset:20480
	ds_read_b128 v[200:203], v145 offset:21504
	ds_read_b128 v[208:211], v145 offset:22528
	ds_read_b128 v[212:215], v145 offset:23552
	global_load_lds_dwordx4 v[234:235], off
	v_lshl_add_u64 v[236:237], s[40:41], 0, v[134:135]
	s_mov_b32 m0, s48
	s_nop 0
	global_load_lds_dwordx4 v[236:237], off
	s_waitcnt vmcnt(10)
	s_barrier
	s_waitcnt lgkmcnt(0)
	s_setprio 1
	s_waitcnt lgkmcnt(0)
	v_mfma_f32_16x16x32_bf16 v[64:67], v[146:149], v[180:183], v[64:67]
	v_mfma_f32_16x16x32_bf16 v[56:59], v[154:157], v[180:183], v[56:59]
	v_mfma_f32_16x16x32_bf16 v[48:51], v[146:149], v[188:191], v[48:51]
	v_mfma_f32_16x16x32_bf16 v[40:43], v[154:157], v[188:191], v[40:43]
	v_mfma_f32_16x16x32_bf16 v[32:35], v[146:149], v[196:199], v[32:35]
	v_mfma_f32_16x16x32_bf16 v[24:27], v[154:157], v[196:199], v[24:27]
	v_mfma_f32_16x16x32_bf16 v[16:19], v[146:149], v[208:211], v[16:19]
	v_mfma_f32_16x16x32_bf16 v[8:11], v[154:157], v[208:211], v[8:11]
	v_mfma_f32_16x16x32_bf16 v[64:67], v[150:153], v[184:187], v[64:67]
	v_mfma_f32_16x16x32_bf16 v[56:59], v[158:161], v[184:187], v[56:59]
	v_mfma_f32_16x16x32_bf16 v[48:51], v[150:153], v[192:195], v[48:51]
	v_mfma_f32_16x16x32_bf16 v[40:43], v[158:161], v[192:195], v[40:43]
	v_mfma_f32_16x16x32_bf16 v[32:35], v[150:153], v[200:203], v[32:35]
	v_mfma_f32_16x16x32_bf16 v[24:27], v[158:161], v[200:203], v[24:27]
	s_setprio 2
	s_barrier
	v_mfma_f32_16x16x32_bf16 v[16:19], v[150:153], v[212:215], v[16:19]
	v_mfma_f32_16x16x32_bf16 v[8:11], v[158:161], v[212:215], v[8:11]
	s_setprio 0
	ds_read_b128 v[146:149], v248 offset:32768
	ds_read_b128 v[150:153], v248 offset:33792
	ds_read_b128 v[154:157], v248 offset:34816
	ds_read_b128 v[158:161], v248 offset:35840
	s_add_u32 s60, s36, 0x80000
	s_addc_u32 s61, s37, 0
	s_add_i32 s62, s62, s47
	s_mov_b32 m0, s62
	s_nop 0
	global_load_lds_dwordx4 v2, s[60:61]
	s_add_i32 m0, s62, 0x2000
	s_nop 0
	global_load_lds_dwordx4 v132, s[60:61]
	s_waitcnt vmcnt(6)
	s_barrier
; #define PG8_STAGE(bufoff, gbase, voff) do { _Pragma("unroll") for (int _i = 0; _i < 2; ++_i) \
;     __builtin_amdgcn_global_load_lds((const unsigned*)((const char*)(gbase) + (voff)[_i]), (LAS unsigned*)(lds + (bufoff) + ldsw + _i * 8192), 16, 0, 0); } while (0)
; #define PG8_LDA(dst, b, h) do { _Pragma("unroll") for (int m = 0; m < 4; ++m) _Pragma("unroll") for (int k = 0; k < 2; ++k) dst[m][k] = *(const LAS bf16x8*)(lds + PG8_SA(b, h) + aoff + m * 2048 + k * 1024); } while (0)
; #define PG8_LDB(dst, b, h) do { _Pragma("unroll") for (int n = 0; n < 2; ++n) _Pragma("unroll") for (int k = 0; k < 2; ++k) dst[n][k] = *(const LAS bf16x8*)(lds + PG8_SB(b, h) + boff + n * 2048 + k * 1024); } while (0)
; #define PG8_MMA(ai, bj, At, Bt) do { __builtin_amdgcn_s_setprio(1); _Pragma("unroll") for (int m = 0; m < 4; ++m) _Pragma("unroll") for (int n = 0; n < 2; ++n) _Pragma("unroll") for (int k = 0; k < 2; ++k) \
;     acc[ai][bj][m][n] = __builtin_amdgcn_mfma_f32_16x16x32_bf16(Bt[n][k], At[m][k], acc[ai][bj][m][n], 0, 0, 0); __builtin_amdgcn_s_setprio(0); } while (0)
; #define PG8_WAIT_V(n) asm volatile("s_waitcnt vmcnt(" #n ")" ::: "memory")
; #define PG8_WAIT_L(n) asm volatile("s_waitcnt lgkmcnt(" #n ")" ::: "memory")
; #define PG8_BAR __builtin_amdgcn_s_barrier()
; #define PG8_SCHED __builtin_amdgcn_sched_barrier(0)
; template <class Epi>
; DI void gemm_phase(LAS unsigned char* lds, const Gemm g, const Epi& E) {
;     ...
;       PG8_WAIT_V(6); PG8_BAR; PG8_MMA(1, 1, At, B1); PG8_BAR;
;       PG8_LDB(B0, 1, 0); PG8_SCHED; PG8_LDA(At, 1, 0); PG8_STAGE(PG8_SA(0, 1), a2 + hstepA, voffA);
;       PG8_WAIT_L(8); PG8_BAR; PG8_WAIT_L(0); PG8_MMA(0, 0, At, B0); PG8_BAR; PG8_SCHED;
;       PG8_LDB(B1, 1, 1); PG8_STAGE(PG8_SB(1, 0), b3, voffB);
;       PG8_BAR; PG8_WAIT_L(0); PG8_MMA(0, 1, At, B1); PG8_BAR;
;       PG8_LDA(At, 1, 1); PG8_STAGE(PG8_SA(1, 0), a3, voffA);
;       PG8_BAR; PG8_WAIT_L(0); PG8_MMA(1, 0, At, B0); PG8_BAR; PG8_SCHED;
	s_setprio 1
	v_mfma_f32_16x16x32_bf16 v[60:63], v[216:219], v[180:183], v[60:63]
	v_mfma_f32_16x16x32_bf16 v[52:55], v[224:227], v[180:183], v[52:55]
	v_mfma_f32_16x16x32_bf16 v[44:47], v[216:219], v[188:191], v[44:47]
	v_mfma_f32_16x16x32_bf16 v[36:39], v[224:227], v[188:191], v[36:39]
	v_mfma_f32_16x16x32_bf16 v[28:31], v[216:219], v[196:199], v[28:31]
	v_mfma_f32_16x16x32_bf16 v[20:23], v[224:227], v[196:199], v[20:23]
	v_mfma_f32_16x16x32_bf16 v[12:15], v[216:219], v[208:211], v[12:15]
	v_mfma_f32_16x16x32_bf16 v[4:7], v[224:227], v[208:211], v[4:7]
	v_mfma_f32_16x16x32_bf16 v[60:63], v[220:223], v[184:187], v[60:63]
	v_mfma_f32_16x16x32_bf16 v[52:55], v[228:231], v[184:187], v[52:55]
	v_mfma_f32_16x16x32_bf16 v[44:47], v[220:223], v[192:195], v[44:47]
	v_mfma_f32_16x16x32_bf16 v[36:39], v[228:231], v[192:195], v[36:39]
	v_mfma_f32_16x16x32_bf16 v[28:31], v[220:223], v[200:203], v[28:31]
	v_mfma_f32_16x16x32_bf16 v[20:23], v[228:231], v[200:203], v[20:23]
	s_setprio 2
	s_barrier
	v_mfma_f32_16x16x32_bf16 v[12:15], v[220:223], v[212:215], v[12:15]
	v_mfma_f32_16x16x32_bf16 v[4:7], v[228:231], v[212:215], v[4:7]
	s_setprio 0
	s_add_i32 s60, 0, 0x18000
	s_add_u32 s40, s40, 0x80000
	s_addc_u32 s41, s41, 0
	s_mov_b32 m0, s49
	ds_read_b128 v[180:183], v145 offset:32768
	ds_read_b128 v[184:187], v145 offset:33792
	ds_read_b128 v[188:191], v145 offset:34816
	ds_read_b128 v[192:195], v145 offset:35840
	ds_read_b128 v[196:199], v145 offset:36864
	ds_read_b128 v[200:203], v145 offset:37888
	ds_read_b128 v[208:211], v145 offset:38912
	ds_read_b128 v[212:215], v145 offset:39936
	global_load_lds_dwordx4 v136, s[40:41]
	s_mov_b32 m0, s50
	s_nop 0
	global_load_lds_dwordx4 v134, s[40:41]
	s_waitcnt lgkmcnt(8)
	s_barrier
	s_waitcnt lgkmcnt(0)
	s_setprio 1
	s_waitcnt lgkmcnt(0)
	v_mfma_f32_16x16x32_bf16 v[128:131], v[146:149], v[180:183], v[128:131]
	v_mfma_f32_16x16x32_bf16 v[120:123], v[154:157], v[180:183], v[120:123]
	v_mfma_f32_16x16x32_bf16 v[112:115], v[146:149], v[188:191], v[112:115]
	v_mfma_f32_16x16x32_bf16 v[104:107], v[154:157], v[188:191], v[104:107]
	v_mfma_f32_16x16x32_bf16 v[96:99], v[146:149], v[196:199], v[96:99]
	v_mfma_f32_16x16x32_bf16 v[88:91], v[154:157], v[196:199], v[88:91]
	v_mfma_f32_16x16x32_bf16 v[80:83], v[146:149], v[208:211], v[80:83]
	v_mfma_f32_16x16x32_bf16 v[72:75], v[154:157], v[208:211], v[72:75]
	v_mfma_f32_16x16x32_bf16 v[128:131], v[150:153], v[184:187], v[128:131]
	v_mfma_f32_16x16x32_bf16 v[120:123], v[158:161], v[184:187], v[120:123]
	v_mfma_f32_16x16x32_bf16 v[112:115], v[150:153], v[192:195], v[112:115]
	v_mfma_f32_16x16x32_bf16 v[104:107], v[158:161], v[192:195], v[104:107]
	v_mfma_f32_16x16x32_bf16 v[96:99], v[150:153], v[200:203], v[96:99]
	v_mfma_f32_16x16x32_bf16 v[88:91], v[158:161], v[200:203], v[88:91]
	s_setprio 2
	s_barrier
	v_mfma_f32_16x16x32_bf16 v[80:83], v[150:153], v[212:215], v[80:83]
	v_mfma_f32_16x16x32_bf16 v[72:75], v[158:161], v[212:215], v[72:75]
	s_setprio 0
	s_add_i32 s40, 0, 0x1c000
	s_add_i32 s41, s60, s47
	v_lshl_add_u64 v[162:163], v[162:163], 0, s[84:85]
	s_mov_b32 m0, s41
	ds_read_b128 v[216:219], v248 offset:49152
	ds_read_b128 v[220:223], v248 offset:50176
	ds_read_b128 v[224:227], v248 offset:51200
	ds_read_b128 v[228:231], v248 offset:52224
	global_load_lds_dwordx4 v[162:163], off
	v_lshl_add_u64 v[162:163], v[232:233], 0, s[84:85]
	s_add_i32 m0, s41, 0x2000
	s_nop 0
	global_load_lds_dwordx4 v[162:163], off
	s_barrier
	s_waitcnt lgkmcnt(0)
	s_setprio 1
	s_waitcnt lgkmcnt(0)
	v_mfma_f32_16x16x32_bf16 v[124:127], v[216:219], v[180:183], v[124:127]
	v_mfma_f32_16x16x32_bf16 v[116:119], v[224:227], v[180:183], v[116:119]
	v_mfma_f32_16x16x32_bf16 v[108:111], v[216:219], v[188:191], v[108:111]
	v_mfma_f32_16x16x32_bf16 v[100:103], v[224:227], v[188:191], v[100:103]
	v_mfma_f32_16x16x32_bf16 v[92:95], v[216:219], v[196:199], v[92:95]
	v_mfma_f32_16x16x32_bf16 v[84:87], v[224:227], v[196:199], v[84:87]
	v_mfma_f32_16x16x32_bf16 v[76:79], v[216:219], v[208:211], v[76:79]
	v_mfma_f32_16x16x32_bf16 v[68:71], v[224:227], v[208:211], v[68:71]
	v_mfma_f32_16x16x32_bf16 v[124:127], v[220:223], v[184:187], v[124:127]
	v_mfma_f32_16x16x32_bf16 v[116:119], v[228:231], v[184:187], v[116:119]
	v_mfma_f32_16x16x32_bf16 v[108:111], v[220:223], v[192:195], v[108:111]
	v_mfma_f32_16x16x32_bf16 v[100:103], v[228:231], v[192:195], v[100:103]
	v_mfma_f32_16x16x32_bf16 v[92:95], v[220:223], v[200:203], v[92:95]
	v_mfma_f32_16x16x32_bf16 v[84:87], v[228:231], v[200:203], v[84:87]
	s_setprio 2
	s_barrier
	v_mfma_f32_16x16x32_bf16 v[76:79], v[220:223], v[212:215], v[76:79]
	v_mfma_f32_16x16x32_bf16 v[68:71], v[228:231], v[212:215], v[68:71]
	s_setprio 0
	s_mov_b32 m0, s51
	v_lshl_add_u64 v[162:163], v[234:235], 0, s[84:85]
	ds_read_b128 v[180:183], v145 offset:49152
	ds_read_b128 v[184:187], v145 offset:50176
	ds_read_b128 v[188:191], v145 offset:51200
	ds_read_b128 v[192:195], v145 offset:52224
	ds_read_b128 v[196:199], v145 offset:53248
	ds_read_b128 v[200:203], v145 offset:54272
	ds_read_b128 v[208:211], v145 offset:55296
	ds_read_b128 v[212:215], v145 offset:56320
	global_load_lds_dwordx4 v[162:163], off
	v_lshl_add_u64 v[162:163], v[236:237], 0, s[84:85]
	s_mov_b32 m0, s52
	s_nop 0
	global_load_lds_dwordx4 v[162:163], off
	s_waitcnt vmcnt(10)
	s_barrier
; DI unsigned cvt_pk_bf16(float lo, float hi) { const f32x2 v = {lo, hi}; const bf16x2_t r = __builtin_convertvector(v, bf16x2_t); return __builtin_bit_cast(unsigned, r); }
; #define PG8_STAGE(bufoff, gbase, voff) do { _Pragma("unroll") for (int _i = 0; _i < 2; ++_i) \
;     __builtin_amdgcn_global_load_lds((const unsigned*)((const char*)(gbase) + (voff)[_i]), (LAS unsigned*)(lds + (bufoff) + ldsw + _i * 8192), 16, 0, 0); } while (0)
; #define PG8_MMA(ai, bj, At, Bt) do { __builtin_amdgcn_s_setprio(1); _Pragma("unroll") for (int m = 0; m < 4; ++m) _Pragma("unroll") for (int n = 0; n < 2; ++n) _Pragma("unroll") for (int k = 0; k < 2; ++k) \
;     acc[ai][bj][m][n] = __builtin_amdgcn_mfma_f32_16x16x32_bf16(Bt[n][k], At[m][k], acc[ai][bj][m][n], 0, 0, 0); __builtin_amdgcn_s_setprio(0); } while (0)
; #define PG8_WAIT_V(n) asm volatile("s_waitcnt vmcnt(" #n ")" ::: "memory")
; #define PG8_WAIT_L(n) asm volatile("s_waitcnt lgkmcnt(" #n ")" ::: "memory")
; #define PG8_BAR __builtin_amdgcn_s_barrier()
; #define PG8_SCHED __builtin_amdgcn_sched_barrier(0)
; DI float silu_f(float g) { return g * __builtin_amdgcn_rcpf(1.0f + __expf(-g)); }
; template <class Epi>
; DI void gemm_phase(LAS unsigned char* lds, const Gemm g, const Epi& E) {
;     ...
;       PG8_BAR; PG8_WAIT_L(0); PG8_MMA(1, 0, At, B0); PG8_BAR; PG8_SCHED;
;       PG8_STAGE(PG8_SB(1, 1), b3 + hstepB, voffB);
;       PG8_WAIT_V(6); PG8_BAR; PG8_MMA(1, 1, At, B1); PG8_BAR;
;     }
;     E(acc, cur, wr, wc, fr, fq);
;   DI void operator()(const f32x4 (&acc)[2][2][4][2], const Unit& u, int wr, int wc, int fr, int fq) const {
;     const int row0 = u.pm * BM + wr * 64 + fr, col0 = u.pn * HALF + wc * 32 + 8 * fq;
; #pragma unroll
;     for (int ai = 0; ai < 2; ++ai)
; #pragma unroll
;       for (int m = 0; m < 4; ++m) {
;         const f32x4 g0 = acc[ai][0][m][0], g1 = acc[ai][0][m][1], u0 = acc[ai][1][m][0], u1 = acc[ai][1][m][1];
;         u32x4 w;
;         w.x = cvt_pk_bf16(silu_f(g0[0]) * u0[0], silu_f(g0[1]) * u0[1]); w.y = cvt_pk_bf16(silu_f(g0[2]) * u0[2], silu_f(g0[3]) * u0[3]);
;         w.z = cvt_pk_bf16(silu_f(g1[0]) * u1[0], silu_f(g1[1]) * u1[1]); w.w = cvt_pk_bf16(silu_f(g1[2]) * u1[2], silu_f(g1[3]) * u1[3]);
;         *(u32x4*)(H + (size_t)(row0 + ai * HALF + m * 16) * DFF + col0) = w;
	s_waitcnt lgkmcnt(0)
	s_setprio 1
	s_waitcnt lgkmcnt(0)
	v_mfma_f32_16x16x32_bf16 v[64:67], v[146:149], v[180:183], v[64:67]
	v_mfma_f32_16x16x32_bf16 v[56:59], v[154:157], v[180:183], v[56:59]
	v_mfma_f32_16x16x32_bf16 v[48:51], v[146:149], v[188:191], v[48:51]
	v_mfma_f32_16x16x32_bf16 v[40:43], v[154:157], v[188:191], v[40:43]
	v_mfma_f32_16x16x32_bf16 v[32:35], v[146:149], v[196:199], v[32:35]
	v_mfma_f32_16x16x32_bf16 v[24:27], v[154:157], v[196:199], v[24:27]
	v_mfma_f32_16x16x32_bf16 v[16:19], v[146:149], v[208:211], v[16:19]
	v_mfma_f32_16x16x32_bf16 v[8:11], v[154:157], v[208:211], v[8:11]
	v_mfma_f32_16x16x32_bf16 v[64:67], v[150:153], v[184:187], v[64:67]
	v_mfma_f32_16x16x32_bf16 v[56:59], v[158:161], v[184:187], v[56:59]
	v_mfma_f32_16x16x32_bf16 v[48:51], v[150:153], v[192:195], v[48:51]
	v_mfma_f32_16x16x32_bf16 v[40:43], v[158:161], v[192:195], v[40:43]
	v_mfma_f32_16x16x32_bf16 v[32:35], v[150:153], v[200:203], v[32:35]
	v_mfma_f32_16x16x32_bf16 v[24:27], v[158:161], v[200:203], v[24:27]
	s_setprio 2
	s_barrier
	v_mfma_f32_16x16x32_bf16 v[16:19], v[150:153], v[212:215], v[16:19]
	v_mfma_f32_16x16x32_bf16 v[8:11], v[158:161], v[212:215], v[8:11]
	s_setprio 0
	ds_read_b128 v[146:149], v248
	ds_read_b128 v[150:153], v248 offset:1024
	ds_read_b128 v[154:157], v248 offset:2048
	ds_read_b128 v[158:161], v248 offset:3072
	s_add_u32 s36, s36, 0x80080
	s_addc_u32 s37, s37, 0
	s_add_i32 s40, s40, s47
	s_mov_b32 m0, s40
	s_nop 0
	global_load_lds_dwordx4 v2, s[36:37]
	s_add_i32 m0, s40, 0x2000
	s_nop 0
	global_load_lds_dwordx4 v132, s[36:37]
	s_waitcnt vmcnt(6)
	s_barrier
	s_setprio 1
	v_mfma_f32_16x16x32_bf16 v[60:63], v[216:219], v[180:183], v[60:63]
	v_mfma_f32_16x16x32_bf16 v[52:55], v[224:227], v[180:183], v[52:55]
	v_mfma_f32_16x16x32_bf16 v[44:47], v[216:219], v[188:191], v[44:47]
	v_mfma_f32_16x16x32_bf16 v[36:39], v[224:227], v[188:191], v[36:39]
	v_mfma_f32_16x16x32_bf16 v[28:31], v[216:219], v[196:199], v[28:31]
	v_mfma_f32_16x16x32_bf16 v[20:23], v[224:227], v[196:199], v[20:23]
	v_mfma_f32_16x16x32_bf16 v[12:15], v[216:219], v[208:211], v[12:15]
	v_mfma_f32_16x16x32_bf16 v[4:7], v[224:227], v[208:211], v[4:7]
	v_mfma_f32_16x16x32_bf16 v[60:63], v[220:223], v[184:187], v[60:63]
	v_mfma_f32_16x16x32_bf16 v[52:55], v[228:231], v[184:187], v[52:55]
	v_mfma_f32_16x16x32_bf16 v[44:47], v[220:223], v[192:195], v[44:47]
	v_mfma_f32_16x16x32_bf16 v[36:39], v[228:231], v[192:195], v[36:39]
	v_mfma_f32_16x16x32_bf16 v[28:31], v[220:223], v[200:203], v[28:31]
	v_mfma_f32_16x16x32_bf16 v[20:23], v[228:231], v[200:203], v[20:23]
	s_setprio 2
	s_barrier
	v_mfma_f32_16x16x32_bf16 v[12:15], v[220:223], v[212:215], v[12:15]
	v_mfma_f32_16x16x32_bf16 v[4:7], v[228:231], v[212:215], v[4:7]
	s_setprio 0
	s_add_i32 s59, s59, 2
	s_add_u32 s30, s30, 0x100
	s_addc_u32 s31, s31, 0
	s_add_u32 s57, s57, 0x100
	s_addc_u32 s58, s58, 0
	s_cmp_gt_u32 s59, 29
	s_cbranch_scc0 .LBB0_190
	s_waitcnt lgkmcnt(0)
	v_mul_f32_e32 v147, 0xbfb8aa3b, v128
	v_exp_f32_e32 v147, v147
	v_lshl_or_b32 v148, s54, 7, v144
	v_lshl_add_u32 v146, s26, 8, v142
	v_ashrrev_i32_e32 v149, 31, v148
	v_add_f32_e32 v147, 1.0, v147
	v_rcp_f32_e32 v150, v147
	v_mul_f32_e32 v147, 0xbfb8aa3b, v129
	v_exp_f32_e32 v147, v147
	s_movk_i32 s3, 0x2c00
	s_movk_i32 s5, 0x2c00
	s_and_b64 vcc, exec, s[38:39]
	v_add_f32_e32 v147, 1.0, v147
	v_rcp_f32_e32 v151, v147
	s_mov_b32 s54, s2
	s_mov_b32 s26, s12
	s_mov_b64 s[36:37], s[22:23]
	v_pk_mul_f32 v[128:129], v[128:129], v[150:151]
	s_nop 0
	v_pk_mul_f32 v[124:125], v[128:129], v[124:125]
	s_nop 0
	v_cvt_pk_bf16_f32 v124, v124, v125
	v_mul_f32_e32 v125, 0xbfb8aa3b, v130
	v_exp_f32_e32 v125, v125
	s_nop 0
	v_add_f32_e32 v125, 1.0, v125
	v_rcp_f32_e32 v128, v125
	v_mul_f32_e32 v125, 0xbfb8aa3b, v131
	v_exp_f32_e32 v125, v125
	s_nop 0
	v_add_f32_e32 v125, 1.0, v125
	v_rcp_f32_e32 v129, v125
	s_nop 0
	v_pk_mul_f32 v[128:129], v[130:131], v[128:129]
	s_nop 0
	v_pk_mul_f32 v[126:127], v[128:129], v[126:127]
	s_nop 0
	v_cvt_pk_bf16_f32 v125, v126, v127
	v_mul_f32_e32 v126, 0xbfb8aa3b, v120
	v_mul_f32_e32 v127, 0xbfb8aa3b, v121
	v_exp_f32_e32 v126, v126
	v_exp_f32_e32 v127, v127
	v_add_f32_e32 v126, 1.0, v126
	v_add_f32_e32 v127, 1.0, v127
	v_rcp_f32_e32 v126, v126
	v_rcp_f32_e32 v127, v127
	s_nop 0
	v_pk_mul_f32 v[120:121], v[120:121], v[126:127]
	s_nop 0
	v_pk_mul_f32 v[116:117], v[120:121], v[116:117]
	s_nop 0
	v_cvt_pk_bf16_f32 v126, v116, v117
	v_mul_f32_e32 v116, 0xbfb8aa3b, v122
	v_mul_f32_e32 v117, 0xbfb8aa3b, v123
	v_exp_f32_e32 v116, v116
	v_exp_f32_e32 v117, v117
	v_add_f32_e32 v116, 1.0, v116
	v_add_f32_e32 v117, 1.0, v117
	v_rcp_f32_e32 v116, v116
	v_rcp_f32_e32 v117, v117
	s_nop 0
	v_pk_mul_f32 v[116:117], v[122:123], v[116:117]
	s_nop 0
	v_pk_mul_f32 v[116:117], v[116:117], v[118:119]
	v_lshlrev_b64 v[118:119], 1, v[148:149]
	v_cvt_pk_bf16_f32 v127, v116, v117
	v_mov_b64_e32 v[116:117], s[0:1]
	v_mad_i64_i32 v[120:121], s[30:31], v146, s3, v[116:117]
	v_lshl_add_u64 v[120:121], v[120:121], 0, v[118:119]
	global_store_dwordx4 v[120:121], v[124:127], off
	v_mul_f32_e32 v120, 0xbfb8aa3b, v112
	v_mul_f32_e32 v121, 0xbfb8aa3b, v113
	v_exp_f32_e32 v120, v120
	v_exp_f32_e32 v121, v121
	v_add_f32_e32 v120, 1.0, v120
	v_add_f32_e32 v121, 1.0, v121
	v_rcp_f32_e32 v120, v120
	v_rcp_f32_e32 v121, v121
	s_nop 0
	v_pk_mul_f32 v[112:113], v[112:113], v[120:121]
	s_nop 0
	v_pk_mul_f32 v[108:109], v[112:113], v[108:109]
	s_nop 0
	v_cvt_pk_bf16_f32 v108, v108, v109
	v_mul_f32_e32 v109, 0xbfb8aa3b, v114
	v_exp_f32_e32 v109, v109
	s_nop 0
	v_add_f32_e32 v109, 1.0, v109
	v_rcp_f32_e32 v112, v109
	v_mul_f32_e32 v109, 0xbfb8aa3b, v115
	v_exp_f32_e32 v109, v109
; DI unsigned cvt_pk_bf16(float lo, float hi) { const f32x2 v = {lo, hi}; const bf16x2_t r = __builtin_convertvector(v, bf16x2_t); return __builtin_bit_cast(unsigned, r); }
; DI float silu_f(float g) { return g * __builtin_amdgcn_rcpf(1.0f + __expf(-g)); }
;   DI void operator()(const f32x4 (&acc)[2][2][4][2], const Unit& u, int wr, int wc, int fr, int fq) const {
;     const int row0 = u.pm * BM + wr * 64 + fr, col0 = u.pn * HALF + wc * 32 + 8 * fq;
; #pragma unroll
;     for (int ai = 0; ai < 2; ++ai)
; #pragma unroll
;       for (int m = 0; m < 4; ++m) {
;         const f32x4 g0 = acc[ai][0][m][0], g1 = acc[ai][0][m][1], u0 = acc[ai][1][m][0], u1 = acc[ai][1][m][1];
;         u32x4 w;
;         w.x = cvt_pk_bf16(silu_f(g0[0]) * u0[0], silu_f(g0[1]) * u0[1]); w.y = cvt_pk_bf16(silu_f(g0[2]) * u0[2], silu_f(g0[3]) * u0[3]);
;         w.z = cvt_pk_bf16(silu_f(g1[0]) * u1[0], silu_f(g1[1]) * u1[1]); w.w = cvt_pk_bf16(silu_f(g1[2]) * u1[2], silu_f(g1[3]) * u1[3]);
;         *(u32x4*)(H + (size_t)(row0 + ai * HALF + m * 16) * DFF + col0) = w;
;       }
	s_nop 0
	v_add_f32_e32 v109, 1.0, v109
	v_rcp_f32_e32 v113, v109
	s_nop 0
	v_pk_mul_f32 v[112:113], v[114:115], v[112:113]
	s_nop 0
	v_pk_mul_f32 v[110:111], v[112:113], v[110:111]
	s_nop 0
	v_cvt_pk_bf16_f32 v109, v110, v111
	v_mul_f32_e32 v110, 0xbfb8aa3b, v104
	v_mul_f32_e32 v111, 0xbfb8aa3b, v105
	v_exp_f32_e32 v110, v110
	v_exp_f32_e32 v111, v111
	v_add_f32_e32 v110, 1.0, v110
	v_add_f32_e32 v111, 1.0, v111
	v_rcp_f32_e32 v110, v110
	v_rcp_f32_e32 v111, v111
	s_nop 0
	v_pk_mul_f32 v[104:105], v[104:105], v[110:111]
	s_nop 0
	v_pk_mul_f32 v[100:101], v[104:105], v[100:101]
	s_nop 0
	v_cvt_pk_bf16_f32 v110, v100, v101
	v_mul_f32_e32 v100, 0xbfb8aa3b, v106
	v_mul_f32_e32 v101, 0xbfb8aa3b, v107
	v_exp_f32_e32 v100, v100
	v_exp_f32_e32 v101, v101
	v_add_f32_e32 v100, 1.0, v100
	v_add_f32_e32 v101, 1.0, v101
	v_rcp_f32_e32 v100, v100
	v_rcp_f32_e32 v101, v101
	s_nop 0
	v_pk_mul_f32 v[100:101], v[106:107], v[100:101]
	s_nop 0
	v_pk_mul_f32 v[100:101], v[100:101], v[102:103]
	s_nop 0
	v_cvt_pk_bf16_f32 v111, v100, v101
	v_or_b32_e32 v100, 16, v146
	v_mad_i64_i32 v[100:101], s[30:31], v100, s3, v[116:117]
	v_lshl_add_u64 v[100:101], v[100:101], 0, v[118:119]
	global_store_dwordx4 v[100:101], v[108:111], off
	v_mul_f32_e32 v100, 0xbfb8aa3b, v96
	v_mul_f32_e32 v101, 0xbfb8aa3b, v97
	v_exp_f32_e32 v100, v100
	v_exp_f32_e32 v101, v101
	v_add_f32_e32 v100, 1.0, v100
	v_add_f32_e32 v101, 1.0, v101
	v_rcp_f32_e32 v100, v100
	v_rcp_f32_e32 v101, v101
	s_nop 0
	v_pk_mul_f32 v[96:97], v[96:97], v[100:101]
	s_nop 0
	v_pk_mul_f32 v[92:93], v[96:97], v[92:93]
	s_nop 0
	v_cvt_pk_bf16_f32 v92, v92, v93
	v_mul_f32_e32 v93, 0xbfb8aa3b, v98
	v_exp_f32_e32 v93, v93
	s_nop 0
	v_add_f32_e32 v93, 1.0, v93
	v_rcp_f32_e32 v96, v93
	v_mul_f32_e32 v93, 0xbfb8aa3b, v99
	v_exp_f32_e32 v93, v93
	s_nop 0
	v_add_f32_e32 v93, 1.0, v93
	v_rcp_f32_e32 v97, v93
	s_nop 0
	v_pk_mul_f32 v[96:97], v[98:99], v[96:97]
	s_nop 0
	v_pk_mul_f32 v[94:95], v[96:97], v[94:95]
	s_nop 0
	v_cvt_pk_bf16_f32 v93, v94, v95
	v_mul_f32_e32 v94, 0xbfb8aa3b, v88
	v_mul_f32_e32 v95, 0xbfb8aa3b, v89
	v_exp_f32_e32 v94, v94
	v_exp_f32_e32 v95, v95
	v_add_f32_e32 v94, 1.0, v94
	v_add_f32_e32 v95, 1.0, v95
	v_rcp_f32_e32 v94, v94
	v_rcp_f32_e32 v95, v95
	s_nop 0
	v_pk_mul_f32 v[88:89], v[88:89], v[94:95]
	s_nop 0
	v_pk_mul_f32 v[84:85], v[88:89], v[84:85]
	s_nop 0
	v_cvt_pk_bf16_f32 v94, v84, v85
	v_mul_f32_e32 v84, 0xbfb8aa3b, v90
	v_mul_f32_e32 v85, 0xbfb8aa3b, v91
	v_exp_f32_e32 v84, v84
	v_exp_f32_e32 v85, v85
	v_add_f32_e32 v84, 1.0, v84
	v_add_f32_e32 v85, 1.0, v85
	v_rcp_f32_e32 v84, v84
	v_rcp_f32_e32 v85, v85
	s_nop 0
	v_pk_mul_f32 v[84:85], v[90:91], v[84:85]
	s_nop 0
	v_pk_mul_f32 v[84:85], v[84:85], v[86:87]
	s_nop 0
	v_cvt_pk_bf16_f32 v95, v84, v85
	v_or_b32_e32 v84, 32, v146
	v_mad_i64_i32 v[84:85], s[30:31], v84, s3, v[116:117]
	v_lshl_add_u64 v[84:85], v[84:85], 0, v[118:119]
	global_store_dwordx4 v[84:85], v[92:95], off
	v_mul_f32_e32 v84, 0xbfb8aa3b, v80
	v_mul_f32_e32 v85, 0xbfb8aa3b, v81
	v_exp_f32_e32 v84, v84
	v_exp_f32_e32 v85, v85
	v_add_f32_e32 v84, 1.0, v84
	v_add_f32_e32 v85, 1.0, v85
	v_rcp_f32_e32 v84, v84
	v_rcp_f32_e32 v85, v85
	s_nop 0
	v_pk_mul_f32 v[80:81], v[80:81], v[84:85]
	s_nop 0
	v_pk_mul_f32 v[76:77], v[80:81], v[76:77]
	s_nop 0
	v_cvt_pk_bf16_f32 v76, v76, v77
	v_mul_f32_e32 v77, 0xbfb8aa3b, v82
	v_exp_f32_e32 v77, v77
	s_nop 0
	v_add_f32_e32 v77, 1.0, v77
	v_rcp_f32_e32 v80, v77
	v_mul_f32_e32 v77, 0xbfb8aa3b, v83
	v_exp_f32_e32 v77, v77
	s_nop 0
	v_add_f32_e32 v77, 1.0, v77
	v_rcp_f32_e32 v81, v77
	s_nop 0
	v_pk_mul_f32 v[80:81], v[82:83], v[80:81]
	s_nop 0
	v_pk_mul_f32 v[78:79], v[80:81], v[78:79]
	s_nop 0
	v_cvt_pk_bf16_f32 v77, v78, v79
	v_mul_f32_e32 v78, 0xbfb8aa3b, v72
	v_mul_f32_e32 v79, 0xbfb8aa3b, v73
	v_exp_f32_e32 v78, v78
	v_exp_f32_e32 v79, v79
	v_add_f32_e32 v78, 1.0, v78
	v_add_f32_e32 v79, 1.0, v79
	v_rcp_f32_e32 v78, v78
	v_rcp_f32_e32 v79, v79
	s_nop 0
	v_pk_mul_f32 v[72:73], v[72:73], v[78:79]
	s_nop 0
	v_pk_mul_f32 v[68:69], v[72:73], v[68:69]
	s_nop 0
	v_cvt_pk_bf16_f32 v78, v68, v69
	v_mul_f32_e32 v68, 0xbfb8aa3b, v74
	v_mul_f32_e32 v69, 0xbfb8aa3b, v75
	v_exp_f32_e32 v68, v68
	v_exp_f32_e32 v69, v69
	v_add_f32_e32 v68, 1.0, v68
	v_add_f32_e32 v69, 1.0, v69
	v_rcp_f32_e32 v68, v68
	v_rcp_f32_e32 v69, v69
	s_nop 0
	v_pk_mul_f32 v[68:69], v[74:75], v[68:69]
	s_nop 0
	v_pk_mul_f32 v[68:69], v[68:69], v[70:71]
	v_add_u32_e32 v70, 0x80, v146
	v_cvt_pk_bf16_f32 v79, v68, v69
	v_or_b32_e32 v68, 48, v146
	v_mad_i64_i32 v[68:69], s[30:31], v68, s3, v[116:117]
	v_lshl_add_u64 v[68:69], v[68:69], 0, v[118:119]
	global_store_dwordx4 v[68:69], v[76:79], off
	v_mul_f32_e32 v68, 0xbfb8aa3b, v64
	v_mul_f32_e32 v69, 0xbfb8aa3b, v65
	v_exp_f32_e32 v68, v68
	v_exp_f32_e32 v69, v69
	v_add_f32_e32 v68, 1.0, v68
	v_add_f32_e32 v69, 1.0, v69
	v_rcp_f32_e32 v68, v68
	v_rcp_f32_e32 v69, v69
	s_nop 0
	v_pk_mul_f32 v[64:65], v[64:65], v[68:69]
	s_nop 0
	v_pk_mul_f32 v[60:61], v[64:65], v[60:61]
	s_nop 0
	v_cvt_pk_bf16_f32 v60, v60, v61
	v_mul_f32_e32 v61, 0xbfb8aa3b, v66
	v_exp_f32_e32 v61, v61
	s_nop 0
	v_add_f32_e32 v61, 1.0, v61
	v_rcp_f32_e32 v64, v61
	v_mul_f32_e32 v61, 0xbfb8aa3b, v67
	v_exp_f32_e32 v61, v61
	s_nop 0
	v_add_f32_e32 v61, 1.0, v61
	v_rcp_f32_e32 v65, v61
	s_nop 0
	v_pk_mul_f32 v[64:65], v[66:67], v[64:65]
	s_nop 0
	v_pk_mul_f32 v[62:63], v[64:65], v[62:63]
	s_nop 0
	v_cvt_pk_bf16_f32 v61, v62, v63
	v_mul_f32_e32 v62, 0xbfb8aa3b, v56
	v_mul_f32_e32 v63, 0xbfb8aa3b, v57
	v_exp_f32_e32 v62, v62
	v_exp_f32_e32 v63, v63
	v_add_f32_e32 v62, 1.0, v62
	v_add_f32_e32 v63, 1.0, v63
	v_rcp_f32_e32 v62, v62
	v_rcp_f32_e32 v63, v63
	s_nop 0
; DI unsigned cvt_pk_bf16(float lo, float hi) { const f32x2 v = {lo, hi}; const bf16x2_t r = __builtin_convertvector(v, bf16x2_t); return __builtin_bit_cast(unsigned, r); }
; #define PG8_WAIT_V(n) asm volatile("s_waitcnt vmcnt(" #n ")" ::: "memory")
; #define PG8_BAR __builtin_amdgcn_s_barrier()
; DI float silu_f(float g) { return g * __builtin_amdgcn_rcpf(1.0f + __expf(-g)); }
; template <class Epi>
; DI void gemm_phase(LAS unsigned char* lds, const Gemm g, const Epi& E) {
;     ...
;     if (!has_next) break;
; #pragma unroll
;     for (int a = 0; a < 2; ++a)
; #pragma unroll
;       for (int b = 0; b < 2; ++b)
; #pragma unroll
;         for (int m = 0; m < 4; ++m)
; #pragma unroll
;           for (int n = 0; n < 2; ++n) acc[a][b][m][n] = (f32x4){0.f, 0.f, 0.f, 0.f};
;     cur = nxt; cA = nA; cB = nB; ++ui;
;   }
;   PG8_WAIT_V(0);
;   if (wr == 0) PG8_BAR;
;   PG8_BAR;
;   DI void operator()(const f32x4 (&acc)[2][2][4][2], const Unit& u, int wr, int wc, int fr, int fq) const {
;     const int row0 = u.pm * BM + wr * 64 + fr, col0 = u.pn * HALF + wc * 32 + 8 * fq;
; #pragma unroll
;     for (int ai = 0; ai < 2; ++ai)
; #pragma unroll
;       for (int m = 0; m < 4; ++m) {
;         const f32x4 g0 = acc[ai][0][m][0], g1 = acc[ai][0][m][1], u0 = acc[ai][1][m][0], u1 = acc[ai][1][m][1];
;         u32x4 w;
;         w.x = cvt_pk_bf16(silu_f(g0[0]) * u0[0], silu_f(g0[1]) * u0[1]); w.y = cvt_pk_bf16(silu_f(g0[2]) * u0[2], silu_f(g0[3]) * u0[3]);
;         w.z = cvt_pk_bf16(silu_f(g1[0]) * u1[0], silu_f(g1[1]) * u1[1]); w.w = cvt_pk_bf16(silu_f(g1[2]) * u1[2], silu_f(g1[3]) * u1[3]);
;         *(u32x4*)(H + (size_t)(row0 + ai * HALF + m * 16) * DFF + col0) = w;
;       }
	v_pk_mul_f32 v[56:57], v[56:57], v[62:63]
	s_nop 0
	v_pk_mul_f32 v[52:53], v[56:57], v[52:53]
	s_nop 0
	v_cvt_pk_bf16_f32 v62, v52, v53
	v_mul_f32_e32 v52, 0xbfb8aa3b, v58
	v_mul_f32_e32 v53, 0xbfb8aa3b, v59
	v_exp_f32_e32 v52, v52
	v_exp_f32_e32 v53, v53
	v_add_f32_e32 v52, 1.0, v52
	v_add_f32_e32 v53, 1.0, v53
	v_rcp_f32_e32 v52, v52
	v_rcp_f32_e32 v53, v53
	s_nop 0
	v_pk_mul_f32 v[52:53], v[58:59], v[52:53]
	s_nop 0
	v_pk_mul_f32 v[52:53], v[52:53], v[54:55]
	s_nop 0
	v_cvt_pk_bf16_f32 v63, v52, v53
	v_mad_i64_i32 v[52:53], s[30:31], v70, s3, v[116:117]
	v_lshl_add_u64 v[52:53], v[52:53], 0, v[118:119]
	global_store_dwordx4 v[52:53], v[60:63], off
	v_mul_f32_e32 v52, 0xbfb8aa3b, v48
	v_mul_f32_e32 v53, 0xbfb8aa3b, v49
	v_exp_f32_e32 v52, v52
	v_exp_f32_e32 v53, v53
	v_add_f32_e32 v52, 1.0, v52
	v_add_f32_e32 v53, 1.0, v53
	v_rcp_f32_e32 v52, v52
	v_rcp_f32_e32 v53, v53
	s_nop 0
	v_pk_mul_f32 v[48:49], v[48:49], v[52:53]
	s_nop 0
	v_pk_mul_f32 v[44:45], v[48:49], v[44:45]
	s_nop 0
	v_cvt_pk_bf16_f32 v44, v44, v45
	v_mul_f32_e32 v45, 0xbfb8aa3b, v50
	v_exp_f32_e32 v45, v45
	s_nop 0
	v_add_f32_e32 v45, 1.0, v45
	v_rcp_f32_e32 v48, v45
	v_mul_f32_e32 v45, 0xbfb8aa3b, v51
	v_exp_f32_e32 v45, v45
	s_nop 0
	v_add_f32_e32 v45, 1.0, v45
	v_rcp_f32_e32 v49, v45
	s_nop 0
	v_pk_mul_f32 v[48:49], v[50:51], v[48:49]
	s_nop 0
	v_pk_mul_f32 v[46:47], v[48:49], v[46:47]
	s_nop 0
	v_cvt_pk_bf16_f32 v45, v46, v47
	v_mul_f32_e32 v46, 0xbfb8aa3b, v40
	v_mul_f32_e32 v47, 0xbfb8aa3b, v41
	v_exp_f32_e32 v46, v46
	v_exp_f32_e32 v47, v47
	v_add_f32_e32 v46, 1.0, v46
	v_add_f32_e32 v47, 1.0, v47
	v_rcp_f32_e32 v46, v46
	v_rcp_f32_e32 v47, v47
	s_nop 0
	v_pk_mul_f32 v[40:41], v[40:41], v[46:47]
	s_nop 0
	v_pk_mul_f32 v[36:37], v[40:41], v[36:37]
	s_nop 0
	v_cvt_pk_bf16_f32 v46, v36, v37
	v_mul_f32_e32 v36, 0xbfb8aa3b, v42
	v_mul_f32_e32 v37, 0xbfb8aa3b, v43
	v_exp_f32_e32 v36, v36
	v_exp_f32_e32 v37, v37
	v_add_f32_e32 v36, 1.0, v36
	v_add_f32_e32 v37, 1.0, v37
	v_rcp_f32_e32 v36, v36
	v_rcp_f32_e32 v37, v37
	s_nop 0
	v_pk_mul_f32 v[36:37], v[42:43], v[36:37]
	s_nop 0
	v_pk_mul_f32 v[36:37], v[36:37], v[38:39]
	s_nop 0
	v_cvt_pk_bf16_f32 v47, v36, v37
	v_add_u32_e32 v36, 0x90, v146
	v_mad_i64_i32 v[36:37], s[30:31], v36, s3, v[116:117]
	v_lshl_add_u64 v[36:37], v[36:37], 0, v[118:119]
	global_store_dwordx4 v[36:37], v[44:47], off
	v_mul_f32_e32 v36, 0xbfb8aa3b, v32
	v_mul_f32_e32 v37, 0xbfb8aa3b, v33
	v_exp_f32_e32 v36, v36
	v_exp_f32_e32 v37, v37
	v_add_f32_e32 v36, 1.0, v36
	v_add_f32_e32 v37, 1.0, v37
	v_rcp_f32_e32 v36, v36
	v_rcp_f32_e32 v37, v37
	s_nop 0
	v_pk_mul_f32 v[32:33], v[32:33], v[36:37]
	s_nop 0
	v_pk_mul_f32 v[28:29], v[32:33], v[28:29]
	s_nop 0
	v_cvt_pk_bf16_f32 v28, v28, v29
	v_mul_f32_e32 v29, 0xbfb8aa3b, v34
	v_exp_f32_e32 v29, v29
	s_nop 0
	v_add_f32_e32 v29, 1.0, v29
	v_rcp_f32_e32 v32, v29
	v_mul_f32_e32 v29, 0xbfb8aa3b, v35
	v_exp_f32_e32 v29, v29
	s_nop 0
	v_add_f32_e32 v29, 1.0, v29
	v_rcp_f32_e32 v33, v29
	s_nop 0
	v_pk_mul_f32 v[32:33], v[34:35], v[32:33]
	s_nop 0
	v_pk_mul_f32 v[30:31], v[32:33], v[30:31]
	s_nop 0
	v_cvt_pk_bf16_f32 v29, v30, v31
	v_mul_f32_e32 v30, 0xbfb8aa3b, v24
	v_mul_f32_e32 v31, 0xbfb8aa3b, v25
	v_exp_f32_e32 v30, v30
	v_exp_f32_e32 v31, v31
	v_add_f32_e32 v30, 1.0, v30
	v_add_f32_e32 v31, 1.0, v31
	v_rcp_f32_e32 v30, v30
	v_rcp_f32_e32 v31, v31
	s_nop 0
	v_pk_mul_f32 v[24:25], v[24:25], v[30:31]
	s_nop 0
	v_pk_mul_f32 v[20:21], v[24:25], v[20:21]
	s_nop 0
	v_cvt_pk_bf16_f32 v30, v20, v21
	v_mul_f32_e32 v20, 0xbfb8aa3b, v26
	v_mul_f32_e32 v21, 0xbfb8aa3b, v27
	v_exp_f32_e32 v20, v20
	v_exp_f32_e32 v21, v21
	v_add_f32_e32 v20, 1.0, v20
	v_add_f32_e32 v21, 1.0, v21
	v_rcp_f32_e32 v20, v20
	v_rcp_f32_e32 v21, v21
	s_nop 0
	v_pk_mul_f32 v[20:21], v[26:27], v[20:21]
	s_nop 0
	v_pk_mul_f32 v[20:21], v[20:21], v[22:23]
	s_nop 0
	v_cvt_pk_bf16_f32 v31, v20, v21
	v_add_u32_e32 v20, 0xa0, v146
	v_mad_i64_i32 v[20:21], s[30:31], v20, s3, v[116:117]
	v_lshl_add_u64 v[20:21], v[20:21], 0, v[118:119]
	global_store_dwordx4 v[20:21], v[28:31], off
	v_mul_f32_e32 v20, 0xbfb8aa3b, v16
	v_mul_f32_e32 v21, 0xbfb8aa3b, v17
	v_exp_f32_e32 v20, v20
	v_exp_f32_e32 v21, v21
	v_add_f32_e32 v20, 1.0, v20
	v_add_f32_e32 v21, 1.0, v21
	v_rcp_f32_e32 v20, v20
	v_rcp_f32_e32 v21, v21
	s_nop 0
	v_pk_mul_f32 v[16:17], v[16:17], v[20:21]
	s_nop 0
	v_pk_mul_f32 v[12:13], v[16:17], v[12:13]
	s_nop 0
	v_cvt_pk_bf16_f32 v12, v12, v13
	v_mul_f32_e32 v13, 0xbfb8aa3b, v18
	v_exp_f32_e32 v13, v13
	s_nop 0
	v_add_f32_e32 v13, 1.0, v13
	v_rcp_f32_e32 v16, v13
	v_mul_f32_e32 v13, 0xbfb8aa3b, v19
	v_exp_f32_e32 v13, v13
	s_nop 0
	v_add_f32_e32 v13, 1.0, v13
	v_rcp_f32_e32 v17, v13
	s_nop 0
	v_pk_mul_f32 v[16:17], v[18:19], v[16:17]
	s_nop 0
	v_pk_mul_f32 v[14:15], v[16:17], v[14:15]
	s_nop 0
	v_cvt_pk_bf16_f32 v13, v14, v15
	v_mul_f32_e32 v14, 0xbfb8aa3b, v8
	v_mul_f32_e32 v15, 0xbfb8aa3b, v9
	v_exp_f32_e32 v14, v14
	v_exp_f32_e32 v15, v15
	v_add_f32_e32 v14, 1.0, v14
	v_add_f32_e32 v15, 1.0, v15
	v_rcp_f32_e32 v14, v14
	v_rcp_f32_e32 v15, v15
	s_nop 0
	v_pk_mul_f32 v[8:9], v[8:9], v[14:15]
	s_nop 0
	v_pk_mul_f32 v[4:5], v[8:9], v[4:5]
	s_nop 0
	v_cvt_pk_bf16_f32 v14, v4, v5
	v_mul_f32_e32 v4, 0xbfb8aa3b, v10
	v_mul_f32_e32 v5, 0xbfb8aa3b, v11
	v_exp_f32_e32 v4, v4
	v_exp_f32_e32 v5, v5
	v_add_f32_e32 v4, 1.0, v4
	v_add_f32_e32 v5, 1.0, v5
	v_rcp_f32_e32 v4, v4
	v_rcp_f32_e32 v5, v5
	s_nop 0
	v_pk_mul_f32 v[4:5], v[10:11], v[4:5]
	s_nop 0
	v_pk_mul_f32 v[4:5], v[4:5], v[6:7]
	s_nop 0
	v_cvt_pk_bf16_f32 v15, v4, v5
	v_add_u32_e32 v4, 0xb0, v146
	v_mad_i64_i32 v[4:5], s[30:31], v4, s3, v[116:117]
	v_lshl_add_u64 v[4:5], v[4:5], 0, v[118:119]
	s_mov_b64 s[30:31], s[18:19]
	global_store_dwordx4 v[4:5], v[12:15], off
	s_cbranch_vccz .LBB0_187
	s_waitcnt vmcnt(0)
	s_cmpk_gt_u32 s25, 0xff
	s_cbranch_scc1 .LBB0_194
	s_barrier

; #define PG8_STAGE(bufoff, gbase, voff) do { _Pragma("unroll") for (int _i = 0; _i < 2; ++_i) \
;     __builtin_amdgcn_global_load_lds((const unsigned*)((const char*)(gbase) + (voff)[_i]), (LAS unsigned*)(lds + (bufoff) + ldsw + _i * 8192), 16, 0, 0); } while (0)
; #define PG8_LDA(dst, b, h) do { _Pragma("unroll") for (int m = 0; m < 4; ++m) _Pragma("unroll") for (int k = 0; k < 2; ++k) dst[m][k] = *(const LAS bf16x8*)(lds + PG8_SA(b, h) + aoff + m * 2048 + k * 1024); } while (0)
; #define PG8_LDB(dst, b, h) do { _Pragma("unroll") for (int n = 0; n < 2; ++n) _Pragma("unroll") for (int k = 0; k < 2; ++k) dst[n][k] = *(const LAS bf16x8*)(lds + PG8_SB(b, h) + boff + n * 2048 + k * 1024); } while (0)
; #define PG8_MMA(ai, bj, At, Bt) do { __builtin_amdgcn_s_setprio(1); _Pragma("unroll") for (int m = 0; m < 4; ++m) _Pragma("unroll") for (int n = 0; n < 2; ++n) _Pragma("unroll") for (int k = 0; k < 2; ++k) \
;     acc[ai][bj][m][n] = __builtin_amdgcn_mfma_f32_16x16x32_bf16(Bt[n][k], At[m][k], acc[ai][bj][m][n], 0, 0, 0); __builtin_amdgcn_s_setprio(0); } while (0)
; #define PG8_WAIT_V(n) asm volatile("s_waitcnt vmcnt(" #n ")" ::: "memory")
; #define PG8_WAIT_L(n) asm volatile("s_waitcnt lgkmcnt(" #n ")" ::: "memory")
; #define PG8_BAR __builtin_amdgcn_s_barrier()
; template <class Epi>
; DI void gemm_phase(LAS unsigned char* lds, const Gemm g, const Epi& E) {
;     ...
;     for (int t = 0; t < nt; t += 2) {
;       const bool last = (t == nt - 2);
;       const char* a1 = cA + (size_t)(t + 1) * kstep;
;       const char* a2 = last ? nA : cA + (size_t)(t + 2) * kstep; const char* b2 = last ? nB : cB + (size_t)(t + 2) * kstep;
;       const char* a3 = a2 + kstep; const char* b3 = b2 + kstep;
;       PG8_LDB(B0, 0, 0); PG8_SCHED; PG8_LDA(At, 0, 0); PG8_STAGE(PG8_SA(1, 1), a1 + hstepA, voffA);
;       PG8_WAIT_L(8); PG8_BAR; PG8_WAIT_L(0); PG8_MMA(0, 0, At, B0); PG8_BAR; PG8_SCHED;
;       PG8_LDB(B1, 0, 1); PG8_STAGE(PG8_SB(0, 0), b2, voffB);
;       PG8_BAR; PG8_WAIT_L(0); PG8_MMA(0, 1, At, B1); PG8_BAR;
;       PG8_LDA(At, 0, 1); PG8_STAGE(PG8_SA(0, 0), a2, voffA);
;       PG8_BAR; PG8_WAIT_L(0); PG8_MMA(1, 0, At, B0); PG8_BAR; PG8_SCHED;
;       PG8_STAGE(PG8_SB(0, 1), b2 + hstepB, voffB);
;       PG8_WAIT_V(6); PG8_BAR; PG8_MMA(1, 1, At, B1); PG8_BAR;
;       PG8_LDB(B0, 1, 0); PG8_SCHED; PG8_LDA(At, 1, 0); PG8_STAGE(PG8_SA(0, 1), a2 + hstepA, voffA);
.LBB0_225:
	s_add_u32 s44, s42, 0xfff80080
	s_addc_u32 s45, s43, -1
	s_add_i32 s67, 0, 0x10000
	s_cmp_eq_u32 s66, 28
	s_cselect_b32 s47, s27, s45
	s_cselect_b32 s46, s41, s44
	s_cselect_b32 s45, s23, s65
	s_cselect_b32 s44, s63, s64
	s_add_i32 m0, s55, 0xc000
	ds_read_b128 v[188:191], v154
	ds_read_b128 v[192:195], v154 offset:1024
	ds_read_b128 v[196:199], v154 offset:2048
	ds_read_b128 v[200:203], v154 offset:3072
	ds_read_b128 v[208:211], v154 offset:4096
	ds_read_b128 v[212:215], v154 offset:5120
	ds_read_b128 v[216:219], v154 offset:6144
	ds_read_b128 v[220:223], v154 offset:7168
	global_load_lds_dwordx4 v144, s[42:43]
	s_add_i32 m0, s55, 0xe000
	s_nop 0
	global_load_lds_dwordx4 v146, s[42:43]
	s_waitcnt lgkmcnt(8)
	s_barrier
	s_waitcnt lgkmcnt(0)
	s_setprio 1
	s_waitcnt lgkmcnt(0)
	v_mfma_f32_16x16x32_bf16 v[128:131], v[156:159], v[188:191], v[128:131]
	v_mfma_f32_16x16x32_bf16 v[124:127], v[180:183], v[188:191], v[124:127]
	v_mfma_f32_16x16x32_bf16 v[120:123], v[156:159], v[196:199], v[120:123]
	v_mfma_f32_16x16x32_bf16 v[116:119], v[180:183], v[196:199], v[116:119]
	v_mfma_f32_16x16x32_bf16 v[104:107], v[156:159], v[208:211], v[104:107]
	v_mfma_f32_16x16x32_bf16 v[100:103], v[180:183], v[208:211], v[100:103]
	v_mfma_f32_16x16x32_bf16 v[88:91], v[156:159], v[216:219], v[88:91]
	v_mfma_f32_16x16x32_bf16 v[84:87], v[180:183], v[216:219], v[84:87]
	v_mfma_f32_16x16x32_bf16 v[128:131], v[160:163], v[192:195], v[128:131]
	v_mfma_f32_16x16x32_bf16 v[124:127], v[184:187], v[192:195], v[124:127]
	v_mfma_f32_16x16x32_bf16 v[120:123], v[160:163], v[200:203], v[120:123]
	v_mfma_f32_16x16x32_bf16 v[116:119], v[184:187], v[200:203], v[116:119]
	v_mfma_f32_16x16x32_bf16 v[104:107], v[160:163], v[212:215], v[104:107]
	v_mfma_f32_16x16x32_bf16 v[100:103], v[184:187], v[212:215], v[100:103]
	s_setprio 2
	s_barrier
	v_mfma_f32_16x16x32_bf16 v[88:91], v[160:163], v[220:223], v[88:91]
	v_mfma_f32_16x16x32_bf16 v[84:87], v[184:187], v[220:223], v[84:87]
	s_setprio 0
	s_add_i32 s70, 0, 0x14000
	s_add_i32 s67, s67, s54
	v_lshl_add_u64 v[148:149], s[44:45], 0, v[136:137]
	s_mov_b32 m0, s67
	ds_read_b128 v[224:227], v248 offset:16384
	ds_read_b128 v[228:231], v248 offset:17408
	ds_read_b128 v[232:235], v248 offset:18432
	ds_read_b128 v[236:239], v248 offset:19456
	global_load_lds_dwordx4 v[148:149], off
	v_lshl_add_u64 v[240:241], s[44:45], 0, v[132:133]
	s_add_i32 m0, s67, 0x2000
	s_nop 0
	global_load_lds_dwordx4 v[240:241], off
	s_barrier
	s_waitcnt lgkmcnt(0)
	s_setprio 1
	s_waitcnt lgkmcnt(0)
	v_mfma_f32_16x16x32_bf16 v[112:115], v[224:227], v[188:191], v[112:115]
	v_mfma_f32_16x16x32_bf16 v[108:111], v[232:235], v[188:191], v[108:111]
	v_mfma_f32_16x16x32_bf16 v[96:99], v[224:227], v[196:199], v[96:99]
	v_mfma_f32_16x16x32_bf16 v[92:95], v[232:235], v[196:199], v[92:95]
	v_mfma_f32_16x16x32_bf16 v[80:83], v[224:227], v[208:211], v[80:83]
	v_mfma_f32_16x16x32_bf16 v[76:79], v[232:235], v[208:211], v[76:79]
	v_mfma_f32_16x16x32_bf16 v[72:75], v[224:227], v[216:219], v[72:75]
	v_mfma_f32_16x16x32_bf16 v[68:71], v[232:235], v[216:219], v[68:71]
	v_mfma_f32_16x16x32_bf16 v[112:115], v[228:231], v[192:195], v[112:115]
	v_mfma_f32_16x16x32_bf16 v[108:111], v[236:239], v[192:195], v[108:111]
	v_mfma_f32_16x16x32_bf16 v[96:99], v[228:231], v[200:203], v[96:99]
	v_mfma_f32_16x16x32_bf16 v[92:95], v[236:239], v[200:203], v[92:95]
	v_mfma_f32_16x16x32_bf16 v[80:83], v[228:231], v[212:215], v[80:83]
	v_mfma_f32_16x16x32_bf16 v[76:79], v[236:239], v[212:215], v[76:79]
	s_setprio 2
	s_barrier
	v_mfma_f32_16x16x32_bf16 v[72:75], v[228:231], v[220:223], v[72:75]
	v_mfma_f32_16x16x32_bf16 v[68:71], v[236:239], v[220:223], v[68:71]
	s_setprio 0
	s_mov_b32 m0, s55
	v_lshl_add_u64 v[242:243], s[46:47], 0, v[138:139]
	ds_read_b128 v[188:191], v154 offset:16384
	ds_read_b128 v[192:195], v154 offset:17408
	ds_read_b128 v[196:199], v154 offset:18432
	ds_read_b128 v[200:203], v154 offset:19456
	ds_read_b128 v[208:211], v154 offset:20480
	ds_read_b128 v[212:215], v154 offset:21504
	ds_read_b128 v[216:219], v154 offset:22528
	ds_read_b128 v[220:223], v154 offset:23552
	global_load_lds_dwordx4 v[242:243], off
	v_lshl_add_u64 v[244:245], s[46:47], 0, v[134:135]
	s_mov_b32 m0, s56
	s_nop 0
	global_load_lds_dwordx4 v[244:245], off
	s_waitcnt vmcnt(10)
	s_barrier
	s_waitcnt lgkmcnt(0)
	s_setprio 1
	s_waitcnt lgkmcnt(0)
	v_mfma_f32_16x16x32_bf16 v[64:67], v[156:159], v[188:191], v[64:67]
	v_mfma_f32_16x16x32_bf16 v[60:63], v[180:183], v[188:191], v[60:63]
	v_mfma_f32_16x16x32_bf16 v[56:59], v[156:159], v[196:199], v[56:59]
	v_mfma_f32_16x16x32_bf16 v[52:55], v[180:183], v[196:199], v[52:55]
	v_mfma_f32_16x16x32_bf16 v[40:43], v[156:159], v[208:211], v[40:43]
	v_mfma_f32_16x16x32_bf16 v[36:39], v[180:183], v[208:211], v[36:39]
	v_mfma_f32_16x16x32_bf16 v[24:27], v[156:159], v[216:219], v[24:27]
	v_mfma_f32_16x16x32_bf16 v[20:23], v[180:183], v[216:219], v[20:23]
	v_mfma_f32_16x16x32_bf16 v[64:67], v[160:163], v[192:195], v[64:67]
	v_mfma_f32_16x16x32_bf16 v[60:63], v[184:187], v[192:195], v[60:63]
	v_mfma_f32_16x16x32_bf16 v[56:59], v[160:163], v[200:203], v[56:59]
	v_mfma_f32_16x16x32_bf16 v[52:55], v[184:187], v[200:203], v[52:55]
	v_mfma_f32_16x16x32_bf16 v[40:43], v[160:163], v[212:215], v[40:43]
	v_mfma_f32_16x16x32_bf16 v[36:39], v[184:187], v[212:215], v[36:39]
	s_setprio 2
	s_barrier
	v_mfma_f32_16x16x32_bf16 v[24:27], v[160:163], v[220:223], v[24:27]
	v_mfma_f32_16x16x32_bf16 v[20:23], v[184:187], v[220:223], v[20:23]
	s_setprio 0
	ds_read_b128 v[156:159], v248 offset:32768
	ds_read_b128 v[160:163], v248 offset:33792
	ds_read_b128 v[180:183], v248 offset:34816
	ds_read_b128 v[184:187], v248 offset:35840
	s_add_u32 s68, s44, 0x80000
	s_addc_u32 s69, s45, 0
	s_add_i32 s67, s70, s54
	s_mov_b32 m0, s67
	s_nop 0
	global_load_lds_dwordx4 v136, s[68:69]
	s_add_i32 m0, s67, 0x2000
	s_nop 0
	global_load_lds_dwordx4 v132, s[68:69]
	s_waitcnt vmcnt(6)
	s_barrier
; #define PG8_STAGE(bufoff, gbase, voff) do { _Pragma("unroll") for (int _i = 0; _i < 2; ++_i) \
;     __builtin_amdgcn_global_load_lds((const unsigned*)((const char*)(gbase) + (voff)[_i]), (LAS unsigned*)(lds + (bufoff) + ldsw + _i * 8192), 16, 0, 0); } while (0)
; #define PG8_LDA(dst, b, h) do { _Pragma("unroll") for (int m = 0; m < 4; ++m) _Pragma("unroll") for (int k = 0; k < 2; ++k) dst[m][k] = *(const LAS bf16x8*)(lds + PG8_SA(b, h) + aoff + m * 2048 + k * 1024); } while (0)
; #define PG8_LDB(dst, b, h) do { _Pragma("unroll") for (int n = 0; n < 2; ++n) _Pragma("unroll") for (int k = 0; k < 2; ++k) dst[n][k] = *(const LAS bf16x8*)(lds + PG8_SB(b, h) + boff + n * 2048 + k * 1024); } while (0)
; #define PG8_MMA(ai, bj, At, Bt) do { __builtin_amdgcn_s_setprio(1); _Pragma("unroll") for (int m = 0; m < 4; ++m) _Pragma("unroll") for (int n = 0; n < 2; ++n) _Pragma("unroll") for (int k = 0; k < 2; ++k) \
;     acc[ai][bj][m][n] = __builtin_amdgcn_mfma_f32_16x16x32_bf16(Bt[n][k], At[m][k], acc[ai][bj][m][n], 0, 0, 0); __builtin_amdgcn_s_setprio(0); } while (0)
; #define PG8_WAIT_V(n) asm volatile("s_waitcnt vmcnt(" #n ")" ::: "memory")
; #define PG8_WAIT_L(n) asm volatile("s_waitcnt lgkmcnt(" #n ")" ::: "memory")
; #define PG8_BAR __builtin_amdgcn_s_barrier()
; #define PG8_SCHED __builtin_amdgcn_sched_barrier(0)
; template <class Epi>
; DI void gemm_phase(LAS unsigned char* lds, const Gemm g, const Epi& E) {
;     ...
;       PG8_WAIT_V(6); PG8_BAR; PG8_MMA(1, 1, At, B1); PG8_BAR;
;       PG8_LDB(B0, 1, 0); PG8_SCHED; PG8_LDA(At, 1, 0); PG8_STAGE(PG8_SA(0, 1), a2 + hstepA, voffA);
;       PG8_WAIT_L(8); PG8_BAR; PG8_WAIT_L(0); PG8_MMA(0, 0, At, B0); PG8_BAR; PG8_SCHED;
;       PG8_LDB(B1, 1, 1); PG8_STAGE(PG8_SB(1, 0), b3, voffB);
;       PG8_BAR; PG8_WAIT_L(0); PG8_MMA(0, 1, At, B1); PG8_BAR;
;       PG8_LDA(At, 1, 1); PG8_STAGE(PG8_SA(1, 0), a3, voffA);
;       PG8_BAR; PG8_WAIT_L(0); PG8_MMA(1, 0, At, B0); PG8_BAR; PG8_SCHED;
	s_setprio 1
	v_mfma_f32_16x16x32_bf16 v[48:51], v[224:227], v[188:191], v[48:51]
	v_mfma_f32_16x16x32_bf16 v[44:47], v[232:235], v[188:191], v[44:47]
	v_mfma_f32_16x16x32_bf16 v[32:35], v[224:227], v[196:199], v[32:35]
	v_mfma_f32_16x16x32_bf16 v[28:31], v[232:235], v[196:199], v[28:31]
	v_mfma_f32_16x16x32_bf16 v[16:19], v[224:227], v[208:211], v[16:19]
	v_mfma_f32_16x16x32_bf16 v[12:15], v[232:235], v[208:211], v[12:15]
	v_mfma_f32_16x16x32_bf16 v[8:11], v[224:227], v[216:219], v[8:11]
	v_mfma_f32_16x16x32_bf16 v[4:7], v[232:235], v[216:219], v[4:7]
	v_mfma_f32_16x16x32_bf16 v[48:51], v[228:231], v[192:195], v[48:51]
	v_mfma_f32_16x16x32_bf16 v[44:47], v[236:239], v[192:195], v[44:47]
	v_mfma_f32_16x16x32_bf16 v[32:35], v[228:231], v[200:203], v[32:35]
	v_mfma_f32_16x16x32_bf16 v[28:31], v[236:239], v[200:203], v[28:31]
	v_mfma_f32_16x16x32_bf16 v[16:19], v[228:231], v[212:215], v[16:19]
	v_mfma_f32_16x16x32_bf16 v[12:15], v[236:239], v[212:215], v[12:15]
	s_setprio 2
	s_barrier
	v_mfma_f32_16x16x32_bf16 v[8:11], v[228:231], v[220:223], v[8:11]
	v_mfma_f32_16x16x32_bf16 v[4:7], v[236:239], v[220:223], v[4:7]
	s_setprio 0
	s_add_i32 s67, 0, 0x18000
	s_add_u32 s46, s46, 0x80000
	s_addc_u32 s47, s47, 0
	s_mov_b32 m0, s57
	ds_read_b128 v[188:191], v154 offset:32768
	ds_read_b128 v[192:195], v154 offset:33792
	ds_read_b128 v[196:199], v154 offset:34816
	ds_read_b128 v[200:203], v154 offset:35840
	ds_read_b128 v[208:211], v154 offset:36864
	ds_read_b128 v[212:215], v154 offset:37888
	ds_read_b128 v[216:219], v154 offset:38912
	ds_read_b128 v[220:223], v154 offset:39936
	global_load_lds_dwordx4 v138, s[46:47]
	s_mov_b32 m0, s58
	s_nop 0
	global_load_lds_dwordx4 v134, s[46:47]
	s_waitcnt lgkmcnt(8)
	s_barrier
	s_waitcnt lgkmcnt(0)
	s_setprio 1
	s_waitcnt lgkmcnt(0)
	v_mfma_f32_16x16x32_bf16 v[128:131], v[156:159], v[188:191], v[128:131]
	v_mfma_f32_16x16x32_bf16 v[124:127], v[180:183], v[188:191], v[124:127]
	v_mfma_f32_16x16x32_bf16 v[120:123], v[156:159], v[196:199], v[120:123]
	v_mfma_f32_16x16x32_bf16 v[116:119], v[180:183], v[196:199], v[116:119]
	v_mfma_f32_16x16x32_bf16 v[104:107], v[156:159], v[208:211], v[104:107]
	v_mfma_f32_16x16x32_bf16 v[100:103], v[180:183], v[208:211], v[100:103]
	v_mfma_f32_16x16x32_bf16 v[88:91], v[156:159], v[216:219], v[88:91]
	v_mfma_f32_16x16x32_bf16 v[84:87], v[180:183], v[216:219], v[84:87]
	v_mfma_f32_16x16x32_bf16 v[128:131], v[160:163], v[192:195], v[128:131]
	v_mfma_f32_16x16x32_bf16 v[124:127], v[184:187], v[192:195], v[124:127]
	v_mfma_f32_16x16x32_bf16 v[120:123], v[160:163], v[200:203], v[120:123]
	v_mfma_f32_16x16x32_bf16 v[116:119], v[184:187], v[200:203], v[116:119]
	v_mfma_f32_16x16x32_bf16 v[104:107], v[160:163], v[212:215], v[104:107]
	v_mfma_f32_16x16x32_bf16 v[100:103], v[184:187], v[212:215], v[100:103]
	s_setprio 2
	s_barrier
	v_mfma_f32_16x16x32_bf16 v[88:91], v[160:163], v[220:223], v[88:91]
	v_mfma_f32_16x16x32_bf16 v[84:87], v[184:187], v[220:223], v[84:87]
	s_setprio 0
	s_add_i32 s46, 0, 0x1c000
	s_add_i32 s47, s67, s54
	v_lshl_add_u64 v[148:149], v[148:149], 0, s[84:85]
	s_mov_b32 m0, s47
	ds_read_b128 v[224:227], v248 offset:49152
	ds_read_b128 v[228:231], v248 offset:50176
	ds_read_b128 v[232:235], v248 offset:51200
	ds_read_b128 v[236:239], v248 offset:52224
	global_load_lds_dwordx4 v[148:149], off
	v_lshl_add_u64 v[148:149], v[240:241], 0, s[84:85]
	s_add_i32 m0, s47, 0x2000
	s_nop 0
	global_load_lds_dwordx4 v[148:149], off
	s_barrier
	s_waitcnt lgkmcnt(0)
	s_setprio 1
	s_waitcnt lgkmcnt(0)
	v_mfma_f32_16x16x32_bf16 v[112:115], v[224:227], v[188:191], v[112:115]
	v_mfma_f32_16x16x32_bf16 v[108:111], v[232:235], v[188:191], v[108:111]
	v_mfma_f32_16x16x32_bf16 v[96:99], v[224:227], v[196:199], v[96:99]
	v_mfma_f32_16x16x32_bf16 v[92:95], v[232:235], v[196:199], v[92:95]
	v_mfma_f32_16x16x32_bf16 v[80:83], v[224:227], v[208:211], v[80:83]
	v_mfma_f32_16x16x32_bf16 v[76:79], v[232:235], v[208:211], v[76:79]
	v_mfma_f32_16x16x32_bf16 v[72:75], v[224:227], v[216:219], v[72:75]
	v_mfma_f32_16x16x32_bf16 v[68:71], v[232:235], v[216:219], v[68:71]
	v_mfma_f32_16x16x32_bf16 v[112:115], v[228:231], v[192:195], v[112:115]
	v_mfma_f32_16x16x32_bf16 v[108:111], v[236:239], v[192:195], v[108:111]
	v_mfma_f32_16x16x32_bf16 v[96:99], v[228:231], v[200:203], v[96:99]
	v_mfma_f32_16x16x32_bf16 v[92:95], v[236:239], v[200:203], v[92:95]
	v_mfma_f32_16x16x32_bf16 v[80:83], v[228:231], v[212:215], v[80:83]
	v_mfma_f32_16x16x32_bf16 v[76:79], v[236:239], v[212:215], v[76:79]
	s_setprio 2
	s_barrier
	v_mfma_f32_16x16x32_bf16 v[72:75], v[228:231], v[220:223], v[72:75]
	v_mfma_f32_16x16x32_bf16 v[68:71], v[236:239], v[220:223], v[68:71]
	s_setprio 0
	s_mov_b32 m0, s60
	v_lshl_add_u64 v[148:149], v[242:243], 0, s[84:85]
	ds_read_b128 v[188:191], v154 offset:49152
	ds_read_b128 v[192:195], v154 offset:50176
	ds_read_b128 v[196:199], v154 offset:51200
	ds_read_b128 v[200:203], v154 offset:52224
	ds_read_b128 v[208:211], v154 offset:53248
	ds_read_b128 v[212:215], v154 offset:54272
	ds_read_b128 v[216:219], v154 offset:55296
	ds_read_b128 v[220:223], v154 offset:56320
	global_load_lds_dwordx4 v[148:149], off
	v_lshl_add_u64 v[148:149], v[244:245], 0, s[84:85]
	s_mov_b32 m0, s61
	s_nop 0
	global_load_lds_dwordx4 v[148:149], off
	s_waitcnt vmcnt(10)
	s_barrier
; #define PG8_STAGE(bufoff, gbase, voff) do { _Pragma("unroll") for (int _i = 0; _i < 2; ++_i) \
;     __builtin_amdgcn_global_load_lds((const unsigned*)((const char*)(gbase) + (voff)[_i]), (LAS unsigned*)(lds + (bufoff) + ldsw + _i * 8192), 16, 0, 0); } while (0)
; #define PG8_MMA(ai, bj, At, Bt) do { __builtin_amdgcn_s_setprio(1); _Pragma("unroll") for (int m = 0; m < 4; ++m) _Pragma("unroll") for (int n = 0; n < 2; ++n) _Pragma("unroll") for (int k = 0; k < 2; ++k) \
;     acc[ai][bj][m][n] = __builtin_amdgcn_mfma_f32_16x16x32_bf16(Bt[n][k], At[m][k], acc[ai][bj][m][n], 0, 0, 0); __builtin_amdgcn_s_setprio(0); } while (0)
; #define PG8_WAIT_V(n) asm volatile("s_waitcnt vmcnt(" #n ")" ::: "memory")
; #define PG8_WAIT_L(n) asm volatile("s_waitcnt lgkmcnt(" #n ")" ::: "memory")
; #define PG8_BAR __builtin_amdgcn_s_barrier()
; #define PG8_SCHED __builtin_amdgcn_sched_barrier(0)
; template <class Epi>
; DI void gemm_phase(LAS unsigned char* lds, const Gemm g, const Epi& E) {
;     ...
;       PG8_BAR; PG8_WAIT_L(0); PG8_MMA(1, 0, At, B0); PG8_BAR; PG8_SCHED;
;       PG8_STAGE(PG8_SB(1, 1), b3 + hstepB, voffB);
;       PG8_WAIT_V(6); PG8_BAR; PG8_MMA(1, 1, At, B1); PG8_BAR;
;     }
;     E(acc, cur, wr, wc, fr, fq);
;   DI void operator()(const f32x4 (&acc)[2][2][4][2], const Unit& u, int wr, int wc, int fr, int fq) const {
;     ...
;       if (wc == 0) {
; #pragma unroll
;         for (int ai = 0; ai < 2; ++ai)
; #pragma unroll
;           for (int m = 0; m < 4; ++m) {
;             float* zp = Z + (size_t)(row0 + ai * HALF + m * 16) * 32 + 8 * fq;
;             *(f32x4*)(zp) = acc[ai][0][m][0]; *(f32x4*)(zp + 4) = acc[ai][0][m][1];
;           }
	s_waitcnt lgkmcnt(0)
	s_setprio 1
	s_waitcnt lgkmcnt(0)
	v_mfma_f32_16x16x32_bf16 v[64:67], v[156:159], v[188:191], v[64:67]
	v_mfma_f32_16x16x32_bf16 v[60:63], v[180:183], v[188:191], v[60:63]
	v_mfma_f32_16x16x32_bf16 v[56:59], v[156:159], v[196:199], v[56:59]
	v_mfma_f32_16x16x32_bf16 v[52:55], v[180:183], v[196:199], v[52:55]
	v_mfma_f32_16x16x32_bf16 v[40:43], v[156:159], v[208:211], v[40:43]
	v_mfma_f32_16x16x32_bf16 v[36:39], v[180:183], v[208:211], v[36:39]
	v_mfma_f32_16x16x32_bf16 v[24:27], v[156:159], v[216:219], v[24:27]
	v_mfma_f32_16x16x32_bf16 v[20:23], v[180:183], v[216:219], v[20:23]
	v_mfma_f32_16x16x32_bf16 v[64:67], v[160:163], v[192:195], v[64:67]
	v_mfma_f32_16x16x32_bf16 v[60:63], v[184:187], v[192:195], v[60:63]
	v_mfma_f32_16x16x32_bf16 v[56:59], v[160:163], v[200:203], v[56:59]
	v_mfma_f32_16x16x32_bf16 v[52:55], v[184:187], v[200:203], v[52:55]
	v_mfma_f32_16x16x32_bf16 v[40:43], v[160:163], v[212:215], v[40:43]
	v_mfma_f32_16x16x32_bf16 v[36:39], v[184:187], v[212:215], v[36:39]
	s_setprio 2
	s_barrier
	v_mfma_f32_16x16x32_bf16 v[24:27], v[160:163], v[220:223], v[24:27]
	v_mfma_f32_16x16x32_bf16 v[20:23], v[184:187], v[220:223], v[20:23]
	s_setprio 0
	ds_read_b128 v[156:159], v248
	ds_read_b128 v[160:163], v248 offset:1024
	ds_read_b128 v[180:183], v248 offset:2048
	ds_read_b128 v[184:187], v248 offset:3072
	s_add_u32 s44, s44, 0x80080
	s_addc_u32 s45, s45, 0
	s_add_i32 s46, s46, s54
	s_mov_b32 m0, s46
	s_nop 0
	global_load_lds_dwordx4 v136, s[44:45]
	s_add_i32 m0, s46, 0x2000
	s_nop 0
	global_load_lds_dwordx4 v132, s[44:45]
	s_waitcnt vmcnt(6)
	s_barrier
	s_setprio 1
	v_mfma_f32_16x16x32_bf16 v[48:51], v[224:227], v[188:191], v[48:51]
	v_mfma_f32_16x16x32_bf16 v[44:47], v[232:235], v[188:191], v[44:47]
	v_mfma_f32_16x16x32_bf16 v[32:35], v[224:227], v[196:199], v[32:35]
	v_mfma_f32_16x16x32_bf16 v[28:31], v[232:235], v[196:199], v[28:31]
	v_mfma_f32_16x16x32_bf16 v[16:19], v[224:227], v[208:211], v[16:19]
	v_mfma_f32_16x16x32_bf16 v[12:15], v[232:235], v[208:211], v[12:15]
	v_mfma_f32_16x16x32_bf16 v[8:11], v[224:227], v[216:219], v[8:11]
	v_mfma_f32_16x16x32_bf16 v[4:7], v[232:235], v[216:219], v[4:7]
	v_mfma_f32_16x16x32_bf16 v[48:51], v[228:231], v[192:195], v[48:51]
	v_mfma_f32_16x16x32_bf16 v[44:47], v[236:239], v[192:195], v[44:47]
	v_mfma_f32_16x16x32_bf16 v[32:35], v[228:231], v[200:203], v[32:35]
	v_mfma_f32_16x16x32_bf16 v[28:31], v[236:239], v[200:203], v[28:31]
	v_mfma_f32_16x16x32_bf16 v[16:19], v[228:231], v[212:215], v[16:19]
	v_mfma_f32_16x16x32_bf16 v[12:15], v[236:239], v[212:215], v[12:15]
	s_setprio 2
	s_barrier
	v_mfma_f32_16x16x32_bf16 v[8:11], v[228:231], v[220:223], v[8:11]
	v_mfma_f32_16x16x32_bf16 v[4:7], v[236:239], v[220:223], v[4:7]
	s_setprio 0
	s_add_i32 s66, s66, 2
	s_add_u32 s42, s42, 0x100
	s_addc_u32 s43, s43, 0
	s_add_u32 s64, s64, 0x100
	s_addc_u32 s65, s65, 0
	s_cmp_gt_u32 s66, 29
	s_cbranch_scc0 .LBB0_225
	s_waitcnt lgkmcnt(0)
	s_lshl_b32 s23, s40, 8
	s_add_i32 s23, s23, s59
	s_cmp_gt_i32 s62, 7
	s_cselect_b64 s[40:41], -1, 0
	s_and_b32 s27, s62, 0x7ffffff8
	s_cmp_lg_u32 s27, 16
	s_cselect_b64 s[42:43], -1, 0
	s_and_b64 s[44:45], s[40:41], s[42:43]
	v_or_b32_e32 v148, s23, v150
	s_mov_b64 s[42:43], -1
	s_and_b64 vcc, exec, s[44:45]
	s_cbranch_vccz .LBB0_234
	s_cmp_gt_u32 s62, 15
	s_cbranch_scc0 .LBB0_231
	s_andn2_b64 vcc, exec, s[18:19]
	s_cbranch_vccnz .LBB0_230
	v_or_b32_e32 v158, 16, v148
	v_ashrrev_i32_e32 v149, 31, v148
	v_ashrrev_i32_e32 v159, 31, v158
	v_lshlrev_b64 v[156:157], 7, v[148:149]
	v_lshlrev_b64 v[158:159], 7, v[158:159]
	v_lshl_add_u64 v[156:157], v[140:141], 0, v[156:157]
	v_lshl_add_u64 v[158:159], v[140:141], 0, v[158:159]
	global_store_dwordx4 v[156:157], v[128:131], off
	global_store_dwordx4 v[156:157], v[124:127], off offset:16
	global_store_dwordx4 v[158:159], v[120:123], off
	global_store_dwordx4 v[158:159], v[116:119], off offset:16
	v_or_b32_e32 v158, 32, v148
	v_ashrrev_i32_e32 v159, 31, v158
	v_lshlrev_b64 v[158:159], 7, v[158:159]
	v_lshl_add_u64 v[158:159], v[140:141], 0, v[158:159]
	global_store_dwordx4 v[158:159], v[104:107], off
	global_store_dwordx4 v[158:159], v[100:103], off offset:16
	v_or_b32_e32 v158, 48, v148
	v_ashrrev_i32_e32 v159, 31, v158
	v_lshlrev_b64 v[158:159], 7, v[158:159]
	s_movk_i32 s27, 0x4000
	v_lshl_add_u64 v[158:159], v[140:141], 0, v[158:159]
	s_mov_b64 s[42:43], 0x4000
	v_add_co_u32_e32 v160, vcc, s27, v156
	global_store_dwordx4 v[158:159], v[88:91], off
	global_store_dwordx4 v[158:159], v[84:87], off offset:16
	v_lshl_add_u64 v[158:159], v[156:157], 0, s[42:43]
	v_addc_co_u32_e32 v161, vcc, 0, v157, vcc
	s_mov_b64 s[42:43], 0x4800
	global_store_dwordx4 v[160:161], v[64:67], off
	global_store_dwordx4 v[158:159], v[60:63], off offset:16
	v_lshl_add_u64 v[158:159], v[156:157], 0, s[42:43]
	global_store_dwordx4 v[160:161], v[56:59], off offset:2048
	global_store_dwordx4 v[158:159], v[52:55], off offset:16
	s_mov_b64 s[42:43], 0x5000
	v_add_co_u32_e32 v160, vcc, 0x5000, v156
	v_lshl_add_u64 v[158:159], v[156:157], 0, s[42:43]
	s_nop 0
	v_addc_co_u32_e32 v161, vcc, 0, v157, vcc
	s_mov_b64 s[42:43], 0x5800
	global_store_dwordx4 v[160:161], v[40:43], off
	global_store_dwordx4 v[158:159], v[36:39], off offset:16
	v_lshl_add_u64 v[156:157], v[156:157], 0, s[42:43]
	global_store_dwordx4 v[160:161], v[24:27], off offset:2048
	global_store_dwordx4 v[156:157], v[20:23], off offset:16

; #define PG8_STAGE(bufoff, gbase, voff) do { _Pragma("unroll") for (int _i = 0; _i < 2; ++_i) \
;     __builtin_amdgcn_global_load_lds((const unsigned*)((const char*)(gbase) + (voff)[_i]), (LAS unsigned*)(lds + (bufoff) + ldsw + _i * 8192), 16, 0, 0); } while (0)
; #define PG8_LDA(dst, b, h) do { _Pragma("unroll") for (int m = 0; m < 4; ++m) _Pragma("unroll") for (int k = 0; k < 2; ++k) dst[m][k] = *(const LAS bf16x8*)(lds + PG8_SA(b, h) + aoff + m * 2048 + k * 1024); } while (0)
; #define PG8_LDB(dst, b, h) do { _Pragma("unroll") for (int n = 0; n < 2; ++n) _Pragma("unroll") for (int k = 0; k < 2; ++k) dst[n][k] = *(const LAS bf16x8*)(lds + PG8_SB(b, h) + boff + n * 2048 + k * 1024); } while (0)
; #define PG8_MMA(ai, bj, At, Bt) do { __builtin_amdgcn_s_setprio(1); _Pragma("unroll") for (int m = 0; m < 4; ++m) _Pragma("unroll") for (int n = 0; n < 2; ++n) _Pragma("unroll") for (int k = 0; k < 2; ++k) \
;     acc[ai][bj][m][n] = __builtin_amdgcn_mfma_f32_16x16x32_bf16(Bt[n][k], At[m][k], acc[ai][bj][m][n], 0, 0, 0); __builtin_amdgcn_s_setprio(0); } while (0)
; #define PG8_WAIT_L(n) asm volatile("s_waitcnt lgkmcnt(" #n ")" ::: "memory")
; #define PG8_BAR __builtin_amdgcn_s_barrier()
; #define PG8_SCHED __builtin_amdgcn_sched_barrier(0)
; template <class Epi>
; DI void gemm_phase(LAS unsigned char* lds, const Gemm g, const Epi& E) {
;     ...
;     for (int t = 0; t < nt; t += 2) {
;       const bool last = (t == nt - 2);
;       const char* a1 = cA + (size_t)(t + 1) * kstep;
;       const char* a2 = last ? nA : cA + (size_t)(t + 2) * kstep; const char* b2 = last ? nB : cB + (size_t)(t + 2) * kstep;
;       const char* a3 = a2 + kstep; const char* b3 = b2 + kstep;
;       PG8_LDB(B0, 0, 0); PG8_SCHED; PG8_LDA(At, 0, 0); PG8_STAGE(PG8_SA(1, 1), a1 + hstepA, voffA);
;       PG8_WAIT_L(8); PG8_BAR; PG8_WAIT_L(0); PG8_MMA(0, 0, At, B0); PG8_BAR; PG8_SCHED;
;       PG8_LDB(B1, 0, 1); PG8_STAGE(PG8_SB(0, 0), b2, voffB);
;       PG8_BAR; PG8_WAIT_L(0); PG8_MMA(0, 1, At, B1); PG8_BAR;
;       PG8_LDA(At, 0, 1); PG8_STAGE(PG8_SA(0, 0), a2, voffA);
;       PG8_BAR; PG8_WAIT_L(0); PG8_MMA(1, 0, At, B0); PG8_BAR; PG8_SCHED;
.LBB0_514:
	s_add_i32 s78, s44, 2
	s_add_u32 s56, s42, 0x80
	s_addc_u32 s45, s43, 0
	s_add_i32 s79, 0, 0x10000
	s_cmp_eq_u32 s72, s44
	s_cselect_b32 s44, s52, s56
	s_cselect_b32 s45, s53, s45
	s_cselect_b32 s57, s55, s59
	s_cselect_b32 s56, s54, s58
	s_add_i32 m0, s64, 0xc000
	ds_read_b128 v[148:151], v195
	ds_read_b128 v[152:155], v195 offset:1024
	ds_read_b128 v[156:159], v195 offset:2048
	ds_read_b128 v[160:163], v195 offset:3072
	ds_read_b128 v[196:199], v195 offset:4096
	ds_read_b128 v[200:203], v195 offset:5120
	ds_read_b128 v[208:211], v195 offset:6144
	ds_read_b128 v[212:215], v195 offset:7168
	global_load_lds_dwordx4 v186, s[42:43]
	s_add_i32 m0, s64, 0xe000
	s_nop 0
	global_load_lds_dwordx4 v188, s[42:43]
	s_waitcnt lgkmcnt(8)
	s_barrier
	s_waitcnt lgkmcnt(0)
	s_setprio 1
	s_waitcnt lgkmcnt(0)
	v_mfma_f32_16x16x32_bf16 v[128:131], v[132:135], v[148:151], v[128:131]
	v_mfma_f32_16x16x32_bf16 v[124:127], v[140:143], v[148:151], v[124:127]
	v_mfma_f32_16x16x32_bf16 v[116:119], v[132:135], v[156:159], v[116:119]
	v_mfma_f32_16x16x32_bf16 v[108:111], v[140:143], v[156:159], v[108:111]
	v_mfma_f32_16x16x32_bf16 v[100:103], v[132:135], v[196:199], v[100:103]
	v_mfma_f32_16x16x32_bf16 v[92:95], v[140:143], v[196:199], v[92:95]
	v_mfma_f32_16x16x32_bf16 v[84:87], v[132:135], v[208:211], v[84:87]
	v_mfma_f32_16x16x32_bf16 v[76:79], v[140:143], v[208:211], v[76:79]
	v_mfma_f32_16x16x32_bf16 v[128:131], v[136:139], v[152:155], v[128:131]
	v_mfma_f32_16x16x32_bf16 v[124:127], v[144:147], v[152:155], v[124:127]
	v_mfma_f32_16x16x32_bf16 v[116:119], v[136:139], v[160:163], v[116:119]
	v_mfma_f32_16x16x32_bf16 v[108:111], v[144:147], v[160:163], v[108:111]
	v_mfma_f32_16x16x32_bf16 v[100:103], v[136:139], v[200:203], v[100:103]
	v_mfma_f32_16x16x32_bf16 v[92:95], v[144:147], v[200:203], v[92:95]
	s_setprio 2
	s_barrier
	v_mfma_f32_16x16x32_bf16 v[84:87], v[136:139], v[212:215], v[84:87]
	v_mfma_f32_16x16x32_bf16 v[76:79], v[144:147], v[212:215], v[76:79]
	s_setprio 0
	s_add_i32 s80, 0, 0x14000
	s_add_i32 s79, s79, s63
	ds_read_b128 v[216:219], v248 offset:16384
	ds_read_b128 v[220:223], v248 offset:17408
	ds_read_b128 v[224:227], v248 offset:18432
	ds_read_b128 v[228:231], v248 offset:19456
	v_lshl_add_u64 v[190:191], s[56:57], 0, v[2:3]
	s_mov_b32 m0, s79
	v_lshl_add_u64 v[232:233], s[56:57], 0, v[184:185]
	global_load_lds_dwordx4 v[190:191], off
	s_add_i32 m0, s79, 0x2000
	s_nop 0
	global_load_lds_dwordx4 v[232:233], off
	s_barrier
	s_waitcnt lgkmcnt(0)
	s_setprio 1
	s_waitcnt lgkmcnt(0)
	v_mfma_f32_16x16x32_bf16 v[120:123], v[216:219], v[148:151], v[120:123]
	v_mfma_f32_16x16x32_bf16 v[112:115], v[224:227], v[148:151], v[112:115]
	v_mfma_f32_16x16x32_bf16 v[104:107], v[216:219], v[156:159], v[104:107]
	v_mfma_f32_16x16x32_bf16 v[96:99], v[224:227], v[156:159], v[96:99]
	v_mfma_f32_16x16x32_bf16 v[88:91], v[216:219], v[196:199], v[88:91]
	v_mfma_f32_16x16x32_bf16 v[80:83], v[224:227], v[196:199], v[80:83]
	v_mfma_f32_16x16x32_bf16 v[72:75], v[216:219], v[208:211], v[72:75]
	v_mfma_f32_16x16x32_bf16 v[68:71], v[224:227], v[208:211], v[68:71]
	v_mfma_f32_16x16x32_bf16 v[120:123], v[220:223], v[152:155], v[120:123]
	v_mfma_f32_16x16x32_bf16 v[112:115], v[228:231], v[152:155], v[112:115]
	v_mfma_f32_16x16x32_bf16 v[104:107], v[220:223], v[160:163], v[104:107]
	v_mfma_f32_16x16x32_bf16 v[96:99], v[228:231], v[160:163], v[96:99]
	v_mfma_f32_16x16x32_bf16 v[88:91], v[220:223], v[200:203], v[88:91]
	v_mfma_f32_16x16x32_bf16 v[80:83], v[228:231], v[200:203], v[80:83]
	s_setprio 2
	s_barrier
	v_mfma_f32_16x16x32_bf16 v[72:75], v[220:223], v[212:215], v[72:75]
	v_mfma_f32_16x16x32_bf16 v[68:71], v[228:231], v[212:215], v[68:71]
	s_setprio 0
	s_mov_b32 m0, s64
	v_lshl_add_u64 v[234:235], s[44:45], 0, v[180:181]
	ds_read_b128 v[148:151], v195 offset:16384
	ds_read_b128 v[152:155], v195 offset:17408
	ds_read_b128 v[156:159], v195 offset:18432
	ds_read_b128 v[160:163], v195 offset:19456
	ds_read_b128 v[196:199], v195 offset:20480
	ds_read_b128 v[200:203], v195 offset:21504
	ds_read_b128 v[208:211], v195 offset:22528
	ds_read_b128 v[212:215], v195 offset:23552
	global_load_lds_dwordx4 v[234:235], off
	v_lshl_add_u64 v[236:237], s[44:45], 0, v[182:183]
	s_mov_b32 m0, s65
	s_nop 0
	global_load_lds_dwordx4 v[236:237], off
	s_waitcnt vmcnt(10)
	s_barrier
	s_waitcnt lgkmcnt(0)
	s_setprio 1
	s_waitcnt lgkmcnt(0)
	v_mfma_f32_16x16x32_bf16 v[64:67], v[132:135], v[148:151], v[64:67]
	v_mfma_f32_16x16x32_bf16 v[60:63], v[140:143], v[148:151], v[60:63]
	v_mfma_f32_16x16x32_bf16 v[56:59], v[132:135], v[156:159], v[56:59]
	v_mfma_f32_16x16x32_bf16 v[48:51], v[140:143], v[156:159], v[48:51]
	v_mfma_f32_16x16x32_bf16 v[40:43], v[132:135], v[196:199], v[40:43]
	v_mfma_f32_16x16x32_bf16 v[32:35], v[140:143], v[196:199], v[32:35]
	v_mfma_f32_16x16x32_bf16 v[24:27], v[132:135], v[208:211], v[24:27]
	v_mfma_f32_16x16x32_bf16 v[16:19], v[140:143], v[208:211], v[16:19]
	v_mfma_f32_16x16x32_bf16 v[64:67], v[136:139], v[152:155], v[64:67]
	v_mfma_f32_16x16x32_bf16 v[60:63], v[144:147], v[152:155], v[60:63]
	v_mfma_f32_16x16x32_bf16 v[56:59], v[136:139], v[160:163], v[56:59]
	v_mfma_f32_16x16x32_bf16 v[48:51], v[144:147], v[160:163], v[48:51]
	v_mfma_f32_16x16x32_bf16 v[40:43], v[136:139], v[200:203], v[40:43]
	v_mfma_f32_16x16x32_bf16 v[32:35], v[144:147], v[200:203], v[32:35]
	s_setprio 2
	s_barrier
; #define PG8_STAGE(bufoff, gbase, voff) do { _Pragma("unroll") for (int _i = 0; _i < 2; ++_i) \
;     __builtin_amdgcn_global_load_lds((const unsigned*)((const char*)(gbase) + (voff)[_i]), (LAS unsigned*)(lds + (bufoff) + ldsw + _i * 8192), 16, 0, 0); } while (0)
; #define PG8_LDA(dst, b, h) do { _Pragma("unroll") for (int m = 0; m < 4; ++m) _Pragma("unroll") for (int k = 0; k < 2; ++k) dst[m][k] = *(const LAS bf16x8*)(lds + PG8_SA(b, h) + aoff + m * 2048 + k * 1024); } while (0)
; #define PG8_LDB(dst, b, h) do { _Pragma("unroll") for (int n = 0; n < 2; ++n) _Pragma("unroll") for (int k = 0; k < 2; ++k) dst[n][k] = *(const LAS bf16x8*)(lds + PG8_SB(b, h) + boff + n * 2048 + k * 1024); } while (0)
; #define PG8_MMA(ai, bj, At, Bt) do { __builtin_amdgcn_s_setprio(1); _Pragma("unroll") for (int m = 0; m < 4; ++m) _Pragma("unroll") for (int n = 0; n < 2; ++n) _Pragma("unroll") for (int k = 0; k < 2; ++k) \
;     acc[ai][bj][m][n] = __builtin_amdgcn_mfma_f32_16x16x32_bf16(Bt[n][k], At[m][k], acc[ai][bj][m][n], 0, 0, 0); __builtin_amdgcn_s_setprio(0); } while (0)
; #define PG8_WAIT_V(n) asm volatile("s_waitcnt vmcnt(" #n ")" ::: "memory")
; #define PG8_WAIT_L(n) asm volatile("s_waitcnt lgkmcnt(" #n ")" ::: "memory")
; #define PG8_BAR __builtin_amdgcn_s_barrier()
; #define PG8_SCHED __builtin_amdgcn_sched_barrier(0)
; template <class Epi>
; DI void gemm_phase(LAS unsigned char* lds, const Gemm g, const Epi& E) {
;     ...
;       PG8_BAR; PG8_WAIT_L(0); PG8_MMA(1, 0, At, B0); PG8_BAR; PG8_SCHED;
;       PG8_STAGE(PG8_SB(0, 1), b2 + hstepB, voffB);
;       PG8_WAIT_V(6); PG8_BAR; PG8_MMA(1, 1, At, B1); PG8_BAR;
;       PG8_LDB(B0, 1, 0); PG8_SCHED; PG8_LDA(At, 1, 0); PG8_STAGE(PG8_SA(0, 1), a2 + hstepA, voffA);
;       PG8_WAIT_L(8); PG8_BAR; PG8_WAIT_L(0); PG8_MMA(0, 0, At, B0); PG8_BAR; PG8_SCHED;
;       PG8_LDB(B1, 1, 1); PG8_STAGE(PG8_SB(1, 0), b3, voffB);
;       PG8_BAR; PG8_WAIT_L(0); PG8_MMA(0, 1, At, B1); PG8_BAR;
	v_mfma_f32_16x16x32_bf16 v[24:27], v[136:139], v[212:215], v[24:27]
	v_mfma_f32_16x16x32_bf16 v[16:19], v[144:147], v[212:215], v[16:19]
	s_setprio 0
	ds_read_b128 v[132:135], v248 offset:32768
	ds_read_b128 v[136:139], v248 offset:33792
	ds_read_b128 v[140:143], v248 offset:34816
	ds_read_b128 v[144:147], v248 offset:35840
	s_add_u32 s56, s56, s18
	s_addc_u32 s57, s57, s19
	s_add_i32 s79, s80, s63
	v_lshl_add_u64 v[238:239], s[56:57], 0, v[2:3]
	s_mov_b32 m0, s79
	v_lshl_add_u64 v[240:241], s[56:57], 0, v[184:185]
	global_load_lds_dwordx4 v[238:239], off
	s_add_i32 m0, s79, 0x2000
	s_nop 0
	global_load_lds_dwordx4 v[240:241], off
	s_waitcnt vmcnt(6)
	s_barrier
	s_setprio 1
	v_mfma_f32_16x16x32_bf16 v[52:55], v[216:219], v[148:151], v[52:55]
	v_mfma_f32_16x16x32_bf16 v[44:47], v[224:227], v[148:151], v[44:47]
	v_mfma_f32_16x16x32_bf16 v[36:39], v[216:219], v[156:159], v[36:39]
	v_mfma_f32_16x16x32_bf16 v[28:31], v[224:227], v[156:159], v[28:31]
	v_mfma_f32_16x16x32_bf16 v[20:23], v[216:219], v[196:199], v[20:23]
	v_mfma_f32_16x16x32_bf16 v[12:15], v[224:227], v[196:199], v[12:15]
	v_mfma_f32_16x16x32_bf16 v[8:11], v[216:219], v[208:211], v[8:11]
	v_mfma_f32_16x16x32_bf16 v[4:7], v[224:227], v[208:211], v[4:7]
	v_mfma_f32_16x16x32_bf16 v[52:55], v[220:223], v[152:155], v[52:55]
	v_mfma_f32_16x16x32_bf16 v[44:47], v[228:231], v[152:155], v[44:47]
	v_mfma_f32_16x16x32_bf16 v[36:39], v[220:223], v[160:163], v[36:39]
	v_mfma_f32_16x16x32_bf16 v[28:31], v[228:231], v[160:163], v[28:31]
	v_mfma_f32_16x16x32_bf16 v[20:23], v[220:223], v[200:203], v[20:23]
	v_mfma_f32_16x16x32_bf16 v[12:15], v[228:231], v[200:203], v[12:15]
	s_setprio 2
	s_barrier
	v_mfma_f32_16x16x32_bf16 v[8:11], v[220:223], v[212:215], v[8:11]
	v_mfma_f32_16x16x32_bf16 v[4:7], v[228:231], v[212:215], v[4:7]
	s_setprio 0
	s_add_i32 s56, 0, 0x18000
	s_add_u32 s44, s44, s8
	s_addc_u32 s45, s45, 0
	s_mov_b32 m0, s66
	ds_read_b128 v[148:151], v195 offset:32768
	ds_read_b128 v[152:155], v195 offset:33792
	ds_read_b128 v[156:159], v195 offset:34816
	ds_read_b128 v[160:163], v195 offset:35840
	ds_read_b128 v[196:199], v195 offset:36864
	ds_read_b128 v[200:203], v195 offset:37888
	ds_read_b128 v[208:211], v195 offset:38912
	ds_read_b128 v[212:215], v195 offset:39936
	global_load_lds_dwordx4 v180, s[44:45]
	s_mov_b32 m0, s67
	s_nop 0
	global_load_lds_dwordx4 v182, s[44:45]
	s_waitcnt lgkmcnt(8)
	s_barrier
	s_waitcnt lgkmcnt(0)
	s_setprio 1
	s_waitcnt lgkmcnt(0)
	v_mfma_f32_16x16x32_bf16 v[128:131], v[132:135], v[148:151], v[128:131]
	v_mfma_f32_16x16x32_bf16 v[124:127], v[140:143], v[148:151], v[124:127]
	v_mfma_f32_16x16x32_bf16 v[116:119], v[132:135], v[156:159], v[116:119]
	v_mfma_f32_16x16x32_bf16 v[108:111], v[140:143], v[156:159], v[108:111]
	v_mfma_f32_16x16x32_bf16 v[100:103], v[132:135], v[196:199], v[100:103]
	v_mfma_f32_16x16x32_bf16 v[92:95], v[140:143], v[196:199], v[92:95]
	v_mfma_f32_16x16x32_bf16 v[84:87], v[132:135], v[208:211], v[84:87]
	v_mfma_f32_16x16x32_bf16 v[76:79], v[140:143], v[208:211], v[76:79]
	v_mfma_f32_16x16x32_bf16 v[128:131], v[136:139], v[152:155], v[128:131]
	v_mfma_f32_16x16x32_bf16 v[124:127], v[144:147], v[152:155], v[124:127]
	v_mfma_f32_16x16x32_bf16 v[116:119], v[136:139], v[160:163], v[116:119]
	v_mfma_f32_16x16x32_bf16 v[108:111], v[144:147], v[160:163], v[108:111]
	v_mfma_f32_16x16x32_bf16 v[100:103], v[136:139], v[200:203], v[100:103]
	v_mfma_f32_16x16x32_bf16 v[92:95], v[144:147], v[200:203], v[92:95]
	s_setprio 2
	s_barrier
	v_mfma_f32_16x16x32_bf16 v[84:87], v[136:139], v[212:215], v[84:87]
	v_mfma_f32_16x16x32_bf16 v[76:79], v[144:147], v[212:215], v[76:79]
	s_setprio 0
	s_add_i32 s44, 0, 0x1c000
	s_add_i32 s45, s56, s63
	v_lshl_add_u64 v[190:191], v[190:191], 0, s[84:85]
	s_mov_b32 m0, s45
	ds_read_b128 v[216:219], v248 offset:49152
	ds_read_b128 v[220:223], v248 offset:50176
	ds_read_b128 v[224:227], v248 offset:51200
	ds_read_b128 v[228:231], v248 offset:52224
	global_load_lds_dwordx4 v[190:191], off
	v_lshl_add_u64 v[190:191], v[232:233], 0, s[84:85]
	s_add_i32 m0, s45, 0x2000
	s_nop 0
	global_load_lds_dwordx4 v[190:191], off
	s_barrier
; #define PG8_STAGE(bufoff, gbase, voff) do { _Pragma("unroll") for (int _i = 0; _i < 2; ++_i) \
;     __builtin_amdgcn_global_load_lds((const unsigned*)((const char*)(gbase) + (voff)[_i]), (LAS unsigned*)(lds + (bufoff) + ldsw + _i * 8192), 16, 0, 0); } while (0)
; #define PG8_LDA(dst, b, h) do { _Pragma("unroll") for (int m = 0; m < 4; ++m) _Pragma("unroll") for (int k = 0; k < 2; ++k) dst[m][k] = *(const LAS bf16x8*)(lds + PG8_SA(b, h) + aoff + m * 2048 + k * 1024); } while (0)
; #define PG8_MMA(ai, bj, At, Bt) do { __builtin_amdgcn_s_setprio(1); _Pragma("unroll") for (int m = 0; m < 4; ++m) _Pragma("unroll") for (int n = 0; n < 2; ++n) _Pragma("unroll") for (int k = 0; k < 2; ++k) \
;     acc[ai][bj][m][n] = __builtin_amdgcn_mfma_f32_16x16x32_bf16(Bt[n][k], At[m][k], acc[ai][bj][m][n], 0, 0, 0); __builtin_amdgcn_s_setprio(0); } while (0)
; #define PG8_WAIT_V(n) asm volatile("s_waitcnt vmcnt(" #n ")" ::: "memory")
; #define PG8_WAIT_L(n) asm volatile("s_waitcnt lgkmcnt(" #n ")" ::: "memory")
; #define PG8_BAR __builtin_amdgcn_s_barrier()
; #define PG8_SCHED __builtin_amdgcn_sched_barrier(0)
; template <class Epi>
; DI void gemm_phase(LAS unsigned char* lds, const Gemm g, const Epi& E) {
;     ...
;       PG8_BAR; PG8_WAIT_L(0); PG8_MMA(0, 1, At, B1); PG8_BAR;
;       PG8_LDA(At, 1, 1); PG8_STAGE(PG8_SA(1, 0), a3, voffA);
;       PG8_BAR; PG8_WAIT_L(0); PG8_MMA(1, 0, At, B0); PG8_BAR; PG8_SCHED;
;       PG8_STAGE(PG8_SB(1, 1), b3 + hstepB, voffB);
;       PG8_WAIT_V(6); PG8_BAR; PG8_MMA(1, 1, At, B1); PG8_BAR;
;     }
;     E(acc, cur, wr, wc, fr, fq);
;   DI void operator()(const f32x4 (&acc)[2][2][4][2], const Unit& u, int wr, int wc, int fr, int fq) const {
;     const int row0 = u.pm * BM + wr * 64 + fr, col0 = u.pn * BM + wc * 32 + 8 * fq;
;     f32x4 bv[2][2], sv[2][2];
; #pragma unroll
;     for (int bj = 0; bj < 2; ++bj)
; #pragma unroll
;       for (int n = 0; n < 2; ++n) {
;         bv[bj][n] = bias ? *(const f32x4*)(bias + col0 + bj * HALF + 4 * n) : (f32x4){0.f, 0.f, 0.f, 0.f};
;         sv[bj][n] = scale ? *(const f32x4*)(scale + col0 + bj * HALF + 4 * n) : (f32x4){1.f, 1.f, 1.f, 1.f};
;       }
	s_waitcnt lgkmcnt(0)
	s_setprio 1
	s_waitcnt lgkmcnt(0)
	v_mfma_f32_16x16x32_bf16 v[120:123], v[216:219], v[148:151], v[120:123]
	v_mfma_f32_16x16x32_bf16 v[112:115], v[224:227], v[148:151], v[112:115]
	v_mfma_f32_16x16x32_bf16 v[104:107], v[216:219], v[156:159], v[104:107]
	v_mfma_f32_16x16x32_bf16 v[96:99], v[224:227], v[156:159], v[96:99]
	v_mfma_f32_16x16x32_bf16 v[88:91], v[216:219], v[196:199], v[88:91]
	v_mfma_f32_16x16x32_bf16 v[80:83], v[224:227], v[196:199], v[80:83]
	v_mfma_f32_16x16x32_bf16 v[72:75], v[216:219], v[208:211], v[72:75]
	v_mfma_f32_16x16x32_bf16 v[68:71], v[224:227], v[208:211], v[68:71]
	v_mfma_f32_16x16x32_bf16 v[120:123], v[220:223], v[152:155], v[120:123]
	v_mfma_f32_16x16x32_bf16 v[112:115], v[228:231], v[152:155], v[112:115]
	v_mfma_f32_16x16x32_bf16 v[104:107], v[220:223], v[160:163], v[104:107]
	v_mfma_f32_16x16x32_bf16 v[96:99], v[228:231], v[160:163], v[96:99]
	v_mfma_f32_16x16x32_bf16 v[88:91], v[220:223], v[200:203], v[88:91]
	v_mfma_f32_16x16x32_bf16 v[80:83], v[228:231], v[200:203], v[80:83]
	s_setprio 2
	s_barrier
	v_mfma_f32_16x16x32_bf16 v[72:75], v[220:223], v[212:215], v[72:75]
	v_mfma_f32_16x16x32_bf16 v[68:71], v[228:231], v[212:215], v[68:71]
	s_setprio 0
	s_mov_b32 m0, s69
	v_lshl_add_u64 v[190:191], v[234:235], 0, s[84:85]
	ds_read_b128 v[148:151], v195 offset:49152
	ds_read_b128 v[152:155], v195 offset:50176
	ds_read_b128 v[156:159], v195 offset:51200
	ds_read_b128 v[160:163], v195 offset:52224
	ds_read_b128 v[196:199], v195 offset:53248
	ds_read_b128 v[200:203], v195 offset:54272
	ds_read_b128 v[208:211], v195 offset:55296
	ds_read_b128 v[212:215], v195 offset:56320
	global_load_lds_dwordx4 v[190:191], off
	v_lshl_add_u64 v[190:191], v[236:237], 0, s[84:85]
	s_mov_b32 m0, s71
	s_nop 0
	global_load_lds_dwordx4 v[190:191], off
	s_waitcnt vmcnt(10)
	s_barrier
	s_waitcnt lgkmcnt(0)
	s_setprio 1
	s_waitcnt lgkmcnt(0)
	v_mfma_f32_16x16x32_bf16 v[64:67], v[132:135], v[148:151], v[64:67]
	v_mfma_f32_16x16x32_bf16 v[60:63], v[140:143], v[148:151], v[60:63]
	v_mfma_f32_16x16x32_bf16 v[56:59], v[132:135], v[156:159], v[56:59]
	v_mfma_f32_16x16x32_bf16 v[48:51], v[140:143], v[156:159], v[48:51]
	v_mfma_f32_16x16x32_bf16 v[40:43], v[132:135], v[196:199], v[40:43]
	v_mfma_f32_16x16x32_bf16 v[32:35], v[140:143], v[196:199], v[32:35]
	v_mfma_f32_16x16x32_bf16 v[24:27], v[132:135], v[208:211], v[24:27]
	v_mfma_f32_16x16x32_bf16 v[16:19], v[140:143], v[208:211], v[16:19]
	v_mfma_f32_16x16x32_bf16 v[64:67], v[136:139], v[152:155], v[64:67]
	v_mfma_f32_16x16x32_bf16 v[60:63], v[144:147], v[152:155], v[60:63]
	v_mfma_f32_16x16x32_bf16 v[56:59], v[136:139], v[160:163], v[56:59]
	v_mfma_f32_16x16x32_bf16 v[48:51], v[144:147], v[160:163], v[48:51]
	v_mfma_f32_16x16x32_bf16 v[40:43], v[136:139], v[200:203], v[40:43]
	v_mfma_f32_16x16x32_bf16 v[32:35], v[144:147], v[200:203], v[32:35]
	s_setprio 2
	s_barrier
	v_mfma_f32_16x16x32_bf16 v[24:27], v[136:139], v[212:215], v[24:27]
	v_mfma_f32_16x16x32_bf16 v[16:19], v[144:147], v[212:215], v[16:19]
	s_setprio 0
	ds_read_b128 v[132:135], v248
	ds_read_b128 v[136:139], v248 offset:1024
	ds_read_b128 v[140:143], v248 offset:2048
	ds_read_b128 v[144:147], v248 offset:3072
	s_add_i32 s44, s44, s63
	v_lshl_add_u64 v[246:247], v[238:239], 0, s[84:85]
	s_mov_b32 m0, s44
	s_nop 0
	global_load_lds_dwordx4 v[246:247], off
	v_lshl_add_u64 v[246:247], v[240:241], 0, s[84:85]
	s_add_i32 m0, s44, 0x2000
	s_nop 0
	global_load_lds_dwordx4 v[246:247], off
	s_waitcnt vmcnt(6)
	s_barrier
	s_setprio 1
	v_mfma_f32_16x16x32_bf16 v[52:55], v[216:219], v[148:151], v[52:55]
	v_mfma_f32_16x16x32_bf16 v[44:47], v[224:227], v[148:151], v[44:47]
	v_mfma_f32_16x16x32_bf16 v[36:39], v[216:219], v[156:159], v[36:39]
	v_mfma_f32_16x16x32_bf16 v[28:31], v[224:227], v[156:159], v[28:31]
	v_mfma_f32_16x16x32_bf16 v[20:23], v[216:219], v[196:199], v[20:23]
	v_mfma_f32_16x16x32_bf16 v[12:15], v[224:227], v[196:199], v[12:15]
	v_mfma_f32_16x16x32_bf16 v[8:11], v[216:219], v[208:211], v[8:11]
	v_mfma_f32_16x16x32_bf16 v[4:7], v[224:227], v[208:211], v[4:7]
	v_mfma_f32_16x16x32_bf16 v[52:55], v[220:223], v[152:155], v[52:55]
	v_mfma_f32_16x16x32_bf16 v[44:47], v[228:231], v[152:155], v[44:47]
	v_mfma_f32_16x16x32_bf16 v[36:39], v[220:223], v[160:163], v[36:39]
	v_mfma_f32_16x16x32_bf16 v[28:31], v[228:231], v[160:163], v[28:31]
	v_mfma_f32_16x16x32_bf16 v[20:23], v[220:223], v[200:203], v[20:23]
	v_mfma_f32_16x16x32_bf16 v[12:15], v[228:231], v[200:203], v[12:15]
	s_setprio 2
	s_barrier
	v_mfma_f32_16x16x32_bf16 v[8:11], v[220:223], v[212:215], v[8:11]
	v_mfma_f32_16x16x32_bf16 v[4:7], v[228:231], v[212:215], v[4:7]
	s_setprio 0
	s_add_u32 s42, s42, 0x100
	s_addc_u32 s43, s43, 0
	s_add_u32 s58, s58, 0x100
	s_addc_u32 s59, s59, 0
	s_cmp_ge_u32 s78, s68
	s_mov_b32 s44, s78
	s_cbranch_scc0 .LBB0_514
	s_waitcnt lgkmcnt(0)
	v_lshl_or_b32 v190, s77, 8, v194
	v_ashrrev_i32_e32 v191, 31, v190
	v_cndmask_b32_e64 v132, 0, 1, s[36:37]
	v_cmp_ne_u32_e64 s[42:43], 1, v132
	s_andn2_b64 vcc, exec, s[36:37]
	v_lshl_add_u64 v[156:157], v[190:191], 2, s[48:49]
	s_cbranch_vccnz .LBB0_517
	global_load_dwordx4 v[132:135], v[156:157], off
	s_branch .LBB0_518
